# all s_setprio flips removed from the nine GEMM K-loops (on top of the pipelined final norm)
# speedup vs baseline: 1.0063x; 1.0063x over previous
.LBB0_577:
	ds_read_b128 v[128:131], v193
	ds_read_b128 v[132:135], v193 offset:1024
	ds_read_b128 v[136:139], v193 offset:2048
	ds_read_b128 v[140:143], v193 offset:3072
	ds_read_b128 v[144:147], v194
	ds_read_b128 v[148:151], v194 offset:1024
	ds_read_b128 v[152:155], v194 offset:2048
	ds_read_b128 v[156:159], v194 offset:3072
	s_add_u32 s35, s42, 0xfff80080
	s_addc_u32 s39, s43, -1
	s_cmp_eq_u32 s31, 4
	s_cselect_b32 s47, s1, s39
	s_cselect_b32 s46, s0, s35
	s_cselect_b32 s45, s37, s23
	s_cselect_b32 s44, s36, s11
	v_lshl_add_u64 v[218:219], s[42:43], 0, v[168:169]
	s_add_i32 m0, s7, 0xc000
	ds_read_b128 v[176:179], v195
	ds_read_b128 v[180:183], v195 offset:1024
	ds_read_b128 v[184:187], v195 offset:2048
	ds_read_b128 v[198:201], v195 offset:3072
	ds_read_b128 v[202:205], v195 offset:4096
	ds_read_b128 v[206:209], v195 offset:5120
	ds_read_b128 v[210:213], v195 offset:6144
	ds_read_b128 v[214:217], v195 offset:7168
	global_load_lds_dwordx4 v[218:219], off
	v_lshl_add_u64 v[218:219], s[42:43], 0, v[170:171]
	s_add_i32 m0, s7, 0xe000
	s_nop 0
	global_load_lds_dwordx4 v[218:219], off
	s_waitcnt vmcnt(8)
	s_waitcnt lgkmcnt(0)
	s_barrier
	s_waitcnt lgkmcnt(0)
	v_mfma_f32_16x16x32_bf16 v[124:127], v[128:131], v[176:179], v[124:127]
	v_mfma_f32_16x16x32_bf16 v[120:123], v[136:139], v[176:179], v[120:123]
	v_mfma_f32_16x16x32_bf16 v[108:111], v[128:131], v[184:187], v[108:111]
	v_mfma_f32_16x16x32_bf16 v[104:107], v[136:139], v[184:187], v[104:107]
	v_mfma_f32_16x16x32_bf16 v[92:95], v[128:131], v[202:205], v[92:95]
	v_mfma_f32_16x16x32_bf16 v[88:91], v[136:139], v[202:205], v[88:91]
	v_mfma_f32_16x16x32_bf16 v[76:79], v[128:131], v[210:213], v[76:79]
	v_mfma_f32_16x16x32_bf16 v[72:75], v[136:139], v[210:213], v[72:75]
	v_mfma_f32_16x16x32_bf16 v[124:127], v[132:135], v[180:183], v[124:127]
	v_mfma_f32_16x16x32_bf16 v[120:123], v[140:143], v[180:183], v[120:123]
	v_mfma_f32_16x16x32_bf16 v[108:111], v[132:135], v[198:201], v[108:111]
	v_mfma_f32_16x16x32_bf16 v[104:107], v[140:143], v[198:201], v[104:107]
	v_mfma_f32_16x16x32_bf16 v[92:95], v[132:135], v[206:209], v[92:95]
	v_mfma_f32_16x16x32_bf16 v[88:91], v[140:143], v[206:209], v[88:91]
	v_mfma_f32_16x16x32_bf16 v[76:79], v[132:135], v[214:217], v[76:79]
	v_mfma_f32_16x16x32_bf16 v[72:75], v[140:143], v[214:217], v[72:75]
	v_mfma_f32_16x16x32_bf16 v[116:119], v[144:147], v[176:179], v[116:119]
	v_mfma_f32_16x16x32_bf16 v[112:115], v[152:155], v[176:179], v[112:115]
	v_mfma_f32_16x16x32_bf16 v[100:103], v[144:147], v[184:187], v[100:103]
	v_mfma_f32_16x16x32_bf16 v[96:99], v[152:155], v[184:187], v[96:99]
	v_mfma_f32_16x16x32_bf16 v[84:87], v[144:147], v[202:205], v[84:87]
	v_mfma_f32_16x16x32_bf16 v[80:83], v[152:155], v[202:205], v[80:83]
	v_mfma_f32_16x16x32_bf16 v[68:71], v[144:147], v[210:213], v[68:71]
	v_mfma_f32_16x16x32_bf16 v[64:67], v[152:155], v[210:213], v[64:67]
	v_mfma_f32_16x16x32_bf16 v[116:119], v[148:151], v[180:183], v[116:119]
	v_mfma_f32_16x16x32_bf16 v[112:115], v[156:159], v[180:183], v[112:115]
	v_mfma_f32_16x16x32_bf16 v[100:103], v[148:151], v[198:201], v[100:103]
	v_mfma_f32_16x16x32_bf16 v[96:99], v[156:159], v[198:201], v[96:99]
	v_mfma_f32_16x16x32_bf16 v[84:87], v[148:151], v[206:209], v[84:87]
	v_mfma_f32_16x16x32_bf16 v[80:83], v[156:159], v[206:209], v[80:83]
	v_mfma_f32_16x16x32_bf16 v[68:71], v[148:151], v[214:217], v[68:71]
	v_mfma_f32_16x16x32_bf16 v[64:67], v[156:159], v[214:217], v[64:67]
	s_barrier
	s_add_i32 s35, s48, s6
	v_lshl_add_u64 v[218:219], s[44:45], 0, v[162:163]
	s_mov_b32 m0, s35
	ds_read_b128 v[176:179], v195 offset:16384
	ds_read_b128 v[180:183], v195 offset:17408
	ds_read_b128 v[184:187], v195 offset:18432
	ds_read_b128 v[198:201], v195 offset:19456
	ds_read_b128 v[202:205], v195 offset:20480
	ds_read_b128 v[206:209], v195 offset:21504
	ds_read_b128 v[210:213], v195 offset:22528
	ds_read_b128 v[214:217], v195 offset:23552
	global_load_lds_dwordx4 v[218:219], off
	s_add_i32 m0, s35, 0x2000
	s_add_u32 s50, s44, 0x20000
	v_lshl_add_u64 v[220:221], s[44:45], 0, v[166:167]
	s_addc_u32 s51, s45, 0
	s_add_i32 s35, s49, s6
	global_load_lds_dwordx4 v[220:221], off
	v_lshl_add_u64 v[222:223], s[50:51], 0, v[162:163]
	s_mov_b32 m0, s35
	v_lshl_add_u64 v[224:225], s[46:47], 0, v[164:165]
	global_load_lds_dwordx4 v[222:223], off
	v_lshl_add_u64 v[222:223], s[50:51], 0, v[166:167]
	s_add_i32 m0, s35, 0x2000
	s_nop 0
	global_load_lds_dwordx4 v[222:223], off
	v_lshl_add_u64 v[222:223], s[46:47], 0, v[160:161]
	s_mov_b32 m0, s7
	s_nop 0
	global_load_lds_dwordx4 v[222:223], off
	s_mov_b32 m0, s8
	s_nop 0
	global_load_lds_dwordx4 v[224:225], off
	s_waitcnt vmcnt(8)
	s_waitcnt lgkmcnt(0)
	s_barrier
	s_waitcnt lgkmcnt(0)
	v_mfma_f32_16x16x32_bf16 v[60:63], v[128:131], v[176:179], v[60:63]
	v_mfma_f32_16x16x32_bf16 v[56:59], v[136:139], v[176:179], v[56:59]
	v_mfma_f32_16x16x32_bf16 v[44:47], v[128:131], v[184:187], v[44:47]
	v_mfma_f32_16x16x32_bf16 v[40:43], v[136:139], v[184:187], v[40:43]
	v_mfma_f32_16x16x32_bf16 v[28:31], v[128:131], v[202:205], v[28:31]
	v_mfma_f32_16x16x32_bf16 v[24:27], v[136:139], v[202:205], v[24:27]
	v_mfma_f32_16x16x32_bf16 v[12:15], v[128:131], v[210:213], v[12:15]
	v_mfma_f32_16x16x32_bf16 v[8:11], v[136:139], v[210:213], v[8:11]
	v_mfma_f32_16x16x32_bf16 v[60:63], v[132:135], v[180:183], v[60:63]
	v_mfma_f32_16x16x32_bf16 v[56:59], v[140:143], v[180:183], v[56:59]
	v_mfma_f32_16x16x32_bf16 v[44:47], v[132:135], v[198:201], v[44:47]
	v_mfma_f32_16x16x32_bf16 v[40:43], v[140:143], v[198:201], v[40:43]
	v_mfma_f32_16x16x32_bf16 v[28:31], v[132:135], v[206:209], v[28:31]
	v_mfma_f32_16x16x32_bf16 v[24:27], v[140:143], v[206:209], v[24:27]
	v_mfma_f32_16x16x32_bf16 v[12:15], v[132:135], v[214:217], v[12:15]
	v_mfma_f32_16x16x32_bf16 v[8:11], v[140:143], v[214:217], v[8:11]
	v_mfma_f32_16x16x32_bf16 v[52:55], v[144:147], v[176:179], v[52:55]
	v_mfma_f32_16x16x32_bf16 v[48:51], v[152:155], v[176:179], v[48:51]
	v_mfma_f32_16x16x32_bf16 v[36:39], v[144:147], v[184:187], v[36:39]
	v_mfma_f32_16x16x32_bf16 v[32:35], v[152:155], v[184:187], v[32:35]
	v_mfma_f32_16x16x32_bf16 v[20:23], v[144:147], v[202:205], v[20:23]
	v_mfma_f32_16x16x32_bf16 v[16:19], v[152:155], v[202:205], v[16:19]
	v_mfma_f32_16x16x32_bf16 v[4:7], v[144:147], v[210:213], v[4:7]
	v_mfma_f32_16x16x32_bf16 v[0:3], v[152:155], v[210:213], v[0:3]
	v_mfma_f32_16x16x32_bf16 v[52:55], v[148:151], v[180:183], v[52:55]
	v_mfma_f32_16x16x32_bf16 v[48:51], v[156:159], v[180:183], v[48:51]
	v_mfma_f32_16x16x32_bf16 v[36:39], v[148:151], v[198:201], v[36:39]
	v_mfma_f32_16x16x32_bf16 v[32:35], v[156:159], v[198:201], v[32:35]
	v_mfma_f32_16x16x32_bf16 v[20:23], v[148:151], v[206:209], v[20:23]
	v_mfma_f32_16x16x32_bf16 v[16:19], v[156:159], v[206:209], v[16:19]
	v_mfma_f32_16x16x32_bf16 v[4:7], v[148:151], v[214:217], v[4:7]
	v_mfma_f32_16x16x32_bf16 v[0:3], v[156:159], v[214:217], v[0:3]
	s_barrier
	s_add_i32 s35, 0, 0x18000
	s_add_i32 s39, 0, 0x1c000
	v_add_u32_e32 v140, s35, v191
	v_add_u32_e32 v156, s39, v191
	ds_read_b128 v[128:131], v140
	ds_read_b128 v[132:135], v140 offset:1024
	ds_read_b128 v[136:139], v140 offset:2048
	ds_read_b128 v[140:143], v140 offset:3072
	ds_read_b128 v[144:147], v156
	ds_read_b128 v[148:151], v156 offset:1024
	ds_read_b128 v[152:155], v156 offset:2048
	ds_read_b128 v[156:159], v156 offset:3072
	s_add_u32 s46, s46, 0x80000
	s_addc_u32 s47, s47, 0
	s_mov_b32 m0, s9
	v_lshl_add_u64 v[226:227], s[46:47], 0, v[160:161]
	ds_read_b128 v[176:179], v195 offset:32768
	ds_read_b128 v[180:183], v195 offset:33792
	ds_read_b128 v[184:187], v195 offset:34816
	ds_read_b128 v[198:201], v195 offset:35840
	ds_read_b128 v[202:205], v195 offset:36864
	ds_read_b128 v[206:209], v195 offset:37888
	ds_read_b128 v[210:213], v195 offset:38912
	ds_read_b128 v[214:217], v195 offset:39936
	global_load_lds_dwordx4 v[226:227], off
	v_lshl_add_u64 v[226:227], s[46:47], 0, v[164:165]
	s_mov_b32 m0, s24
	s_nop 0
	global_load_lds_dwordx4 v[226:227], off
	s_waitcnt vmcnt(8)
	s_waitcnt lgkmcnt(0)
	s_barrier
	s_waitcnt lgkmcnt(0)
	v_mfma_f32_16x16x32_bf16 v[124:127], v[128:131], v[176:179], v[124:127]
	v_mfma_f32_16x16x32_bf16 v[120:123], v[136:139], v[176:179], v[120:123]
	v_mfma_f32_16x16x32_bf16 v[108:111], v[128:131], v[184:187], v[108:111]
	v_mfma_f32_16x16x32_bf16 v[104:107], v[136:139], v[184:187], v[104:107]
	v_mfma_f32_16x16x32_bf16 v[92:95], v[128:131], v[202:205], v[92:95]
	v_mfma_f32_16x16x32_bf16 v[88:91], v[136:139], v[202:205], v[88:91]
	v_mfma_f32_16x16x32_bf16 v[76:79], v[128:131], v[210:213], v[76:79]
	v_mfma_f32_16x16x32_bf16 v[72:75], v[136:139], v[210:213], v[72:75]
	v_mfma_f32_16x16x32_bf16 v[124:127], v[132:135], v[180:183], v[124:127]
	v_mfma_f32_16x16x32_bf16 v[120:123], v[140:143], v[180:183], v[120:123]
	v_mfma_f32_16x16x32_bf16 v[108:111], v[132:135], v[198:201], v[108:111]
	v_mfma_f32_16x16x32_bf16 v[104:107], v[140:143], v[198:201], v[104:107]
	v_mfma_f32_16x16x32_bf16 v[92:95], v[132:135], v[206:209], v[92:95]
	v_mfma_f32_16x16x32_bf16 v[88:91], v[140:143], v[206:209], v[88:91]
	v_mfma_f32_16x16x32_bf16 v[76:79], v[132:135], v[214:217], v[76:79]
	v_mfma_f32_16x16x32_bf16 v[72:75], v[140:143], v[214:217], v[72:75]
	v_mfma_f32_16x16x32_bf16 v[116:119], v[144:147], v[176:179], v[116:119]
	v_mfma_f32_16x16x32_bf16 v[112:115], v[152:155], v[176:179], v[112:115]
	v_mfma_f32_16x16x32_bf16 v[100:103], v[144:147], v[184:187], v[100:103]
	v_mfma_f32_16x16x32_bf16 v[96:99], v[152:155], v[184:187], v[96:99]
	v_mfma_f32_16x16x32_bf16 v[84:87], v[144:147], v[202:205], v[84:87]
	v_mfma_f32_16x16x32_bf16 v[80:83], v[152:155], v[202:205], v[80:83]
	v_mfma_f32_16x16x32_bf16 v[68:71], v[144:147], v[210:213], v[68:71]
	v_mfma_f32_16x16x32_bf16 v[64:67], v[152:155], v[210:213], v[64:67]
	v_mfma_f32_16x16x32_bf16 v[116:119], v[148:151], v[180:183], v[116:119]
	v_mfma_f32_16x16x32_bf16 v[112:115], v[156:159], v[180:183], v[112:115]
	v_mfma_f32_16x16x32_bf16 v[100:103], v[148:151], v[198:201], v[100:103]
	v_mfma_f32_16x16x32_bf16 v[96:99], v[156:159], v[198:201], v[96:99]
	v_mfma_f32_16x16x32_bf16 v[84:87], v[148:151], v[206:209], v[84:87]
	v_mfma_f32_16x16x32_bf16 v[80:83], v[156:159], v[206:209], v[80:83]
	v_mfma_f32_16x16x32_bf16 v[68:71], v[148:151], v[214:217], v[68:71]
	v_mfma_f32_16x16x32_bf16 v[64:67], v[156:159], v[214:217], v[64:67]
	s_barrier
	s_add_i32 s35, s35, s6
	v_lshl_add_u64 v[218:219], v[218:219], 0, s[16:17]
	s_mov_b32 m0, s35
	ds_read_b128 v[176:179], v195 offset:49152
	ds_read_b128 v[180:183], v195 offset:50176
	ds_read_b128 v[184:187], v195 offset:51200
	ds_read_b128 v[198:201], v195 offset:52224
	ds_read_b128 v[202:205], v195 offset:53248
	ds_read_b128 v[206:209], v195 offset:54272
	ds_read_b128 v[210:213], v195 offset:55296
	ds_read_b128 v[214:217], v195 offset:56320
	global_load_lds_dwordx4 v[218:219], off
	s_add_i32 m0, s35, 0x2000
	s_add_u32 s44, s44, 0x20080
	v_lshl_add_u64 v[218:219], v[220:221], 0, s[16:17]
	s_addc_u32 s45, s45, 0
	s_add_i32 s35, s39, s6
	global_load_lds_dwordx4 v[218:219], off
	v_lshl_add_u64 v[218:219], s[44:45], 0, v[162:163]
	s_mov_b32 m0, s35
	s_nop 0
	global_load_lds_dwordx4 v[218:219], off
	v_lshl_add_u64 v[218:219], s[44:45], 0, v[166:167]
	s_add_i32 m0, s35, 0x2000
	s_nop 0
	global_load_lds_dwordx4 v[218:219], off
	v_lshl_add_u64 v[218:219], v[222:223], 0, s[16:17]
	s_mov_b32 m0, s28
	s_nop 0
	global_load_lds_dwordx4 v[218:219], off
	v_lshl_add_u64 v[218:219], v[224:225], 0, s[16:17]
	s_mov_b32 m0, s29
	s_nop 0
	global_load_lds_dwordx4 v[218:219], off
	s_waitcnt vmcnt(8)
	s_waitcnt lgkmcnt(0)
	s_barrier
	s_waitcnt lgkmcnt(0)
	v_mfma_f32_16x16x32_bf16 v[60:63], v[128:131], v[176:179], v[60:63]
	v_mfma_f32_16x16x32_bf16 v[56:59], v[136:139], v[176:179], v[56:59]
	v_mfma_f32_16x16x32_bf16 v[44:47], v[128:131], v[184:187], v[44:47]
	v_mfma_f32_16x16x32_bf16 v[40:43], v[136:139], v[184:187], v[40:43]
	v_mfma_f32_16x16x32_bf16 v[28:31], v[128:131], v[202:205], v[28:31]
	v_mfma_f32_16x16x32_bf16 v[24:27], v[136:139], v[202:205], v[24:27]
	v_mfma_f32_16x16x32_bf16 v[12:15], v[128:131], v[210:213], v[12:15]
	v_mfma_f32_16x16x32_bf16 v[8:11], v[136:139], v[210:213], v[8:11]
	v_mfma_f32_16x16x32_bf16 v[60:63], v[132:135], v[180:183], v[60:63]
	v_mfma_f32_16x16x32_bf16 v[56:59], v[140:143], v[180:183], v[56:59]
	v_mfma_f32_16x16x32_bf16 v[44:47], v[132:135], v[198:201], v[44:47]
	v_mfma_f32_16x16x32_bf16 v[40:43], v[140:143], v[198:201], v[40:43]
	v_mfma_f32_16x16x32_bf16 v[28:31], v[132:135], v[206:209], v[28:31]
	v_mfma_f32_16x16x32_bf16 v[24:27], v[140:143], v[206:209], v[24:27]
	v_mfma_f32_16x16x32_bf16 v[12:15], v[132:135], v[214:217], v[12:15]
	v_mfma_f32_16x16x32_bf16 v[8:11], v[140:143], v[214:217], v[8:11]
	v_mfma_f32_16x16x32_bf16 v[52:55], v[144:147], v[176:179], v[52:55]
	v_mfma_f32_16x16x32_bf16 v[48:51], v[152:155], v[176:179], v[48:51]
	v_mfma_f32_16x16x32_bf16 v[36:39], v[144:147], v[184:187], v[36:39]
	v_mfma_f32_16x16x32_bf16 v[32:35], v[152:155], v[184:187], v[32:35]
	v_mfma_f32_16x16x32_bf16 v[20:23], v[144:147], v[202:205], v[20:23]
	v_mfma_f32_16x16x32_bf16 v[16:19], v[152:155], v[202:205], v[16:19]
	v_mfma_f32_16x16x32_bf16 v[4:7], v[144:147], v[210:213], v[4:7]
	v_mfma_f32_16x16x32_bf16 v[0:3], v[152:155], v[210:213], v[0:3]
	v_mfma_f32_16x16x32_bf16 v[52:55], v[148:151], v[180:183], v[52:55]
	v_mfma_f32_16x16x32_bf16 v[48:51], v[156:159], v[180:183], v[48:51]
	v_mfma_f32_16x16x32_bf16 v[36:39], v[148:151], v[198:201], v[36:39]
	v_mfma_f32_16x16x32_bf16 v[32:35], v[156:159], v[198:201], v[32:35]
	v_mfma_f32_16x16x32_bf16 v[20:23], v[148:151], v[206:209], v[20:23]
	v_mfma_f32_16x16x32_bf16 v[16:19], v[156:159], v[206:209], v[16:19]
	v_mfma_f32_16x16x32_bf16 v[4:7], v[148:151], v[214:217], v[4:7]
	v_mfma_f32_16x16x32_bf16 v[0:3], v[156:159], v[214:217], v[0:3]
	s_barrier
	s_add_i32 s31, s31, 2
	s_add_u32 s42, s42, 0x100
	s_addc_u32 s43, s43, 0
	s_add_u32 s11, s11, 0x100
	s_addc_u32 s23, s23, 0
	s_cmp_gt_u32 s31, 5
	s_cbranch_scc0 .LBB0_577
	s_and_b64 vcc, exec, s[18:19]
	s_cbranch_vccz .LBB0_580
	s_barrier

.LBB0_664:
	ds_read_b128 v[156:159], v151
	ds_read_b128 v[160:163], v151 offset:1024
	ds_read_b128 v[164:167], v151 offset:2048
	ds_read_b128 v[168:171], v151 offset:3072
	ds_read_b128 v[172:175], v152
	ds_read_b128 v[176:179], v152 offset:1024
	ds_read_b128 v[180:183], v152 offset:2048
	ds_read_b128 v[184:187], v152 offset:3072
	s_add_u32 s22, s20, 0xfff80080
	s_addc_u32 s23, s21, -1
	s_cmp_eq_u32 s48, 28
	s_cselect_b32 s31, s13, s23
	s_cselect_b32 s30, s44, s22
	s_cselect_b32 s23, s15, s47
	s_cselect_b32 s22, s45, s46
	v_lshl_add_u64 v[146:147], s[20:21], 0, v[138:139]
	s_add_i32 m0, s11, 0xc000
	ds_read_b128 v[190:193], v153
	ds_read_b128 v[194:197], v153 offset:1024
	ds_read_b128 v[198:201], v153 offset:2048
	ds_read_b128 v[202:205], v153 offset:3072
	ds_read_b128 v[206:209], v153 offset:4096
	ds_read_b128 v[210:213], v153 offset:5120
	ds_read_b128 v[214:217], v153 offset:6144
	ds_read_b128 v[218:221], v153 offset:7168
	global_load_lds_dwordx4 v[146:147], off
	v_lshl_add_u64 v[146:147], s[20:21], 0, v[140:141]
	s_add_i32 m0, s11, 0xe000
	s_nop 0
	global_load_lds_dwordx4 v[146:147], off
	s_waitcnt vmcnt(8)
	s_waitcnt lgkmcnt(0)
	s_barrier
	s_waitcnt lgkmcnt(0)
	v_mfma_f32_16x16x32_bf16 v[116:119], v[156:159], v[190:193], v[116:119]
	v_mfma_f32_16x16x32_bf16 v[112:115], v[164:167], v[190:193], v[112:115]
	v_mfma_f32_16x16x32_bf16 v[100:103], v[156:159], v[198:201], v[100:103]
	v_mfma_f32_16x16x32_bf16 v[96:99], v[164:167], v[198:201], v[96:99]
	v_mfma_f32_16x16x32_bf16 v[84:87], v[156:159], v[206:209], v[84:87]
	v_mfma_f32_16x16x32_bf16 v[80:83], v[164:167], v[206:209], v[80:83]
	v_mfma_f32_16x16x32_bf16 v[68:71], v[156:159], v[214:217], v[68:71]
	v_mfma_f32_16x16x32_bf16 v[64:67], v[164:167], v[214:217], v[64:67]
	v_mfma_f32_16x16x32_bf16 v[116:119], v[160:163], v[194:197], v[116:119]
	v_mfma_f32_16x16x32_bf16 v[112:115], v[168:171], v[194:197], v[112:115]
	v_mfma_f32_16x16x32_bf16 v[100:103], v[160:163], v[202:205], v[100:103]
	v_mfma_f32_16x16x32_bf16 v[96:99], v[168:171], v[202:205], v[96:99]
	v_mfma_f32_16x16x32_bf16 v[84:87], v[160:163], v[210:213], v[84:87]
	v_mfma_f32_16x16x32_bf16 v[80:83], v[168:171], v[210:213], v[80:83]
	v_mfma_f32_16x16x32_bf16 v[68:71], v[160:163], v[218:221], v[68:71]
	v_mfma_f32_16x16x32_bf16 v[64:67], v[168:171], v[218:221], v[64:67]
	v_mfma_f32_16x16x32_bf16 v[124:127], v[172:175], v[190:193], v[124:127]
	v_mfma_f32_16x16x32_bf16 v[120:123], v[180:183], v[190:193], v[120:123]
	v_mfma_f32_16x16x32_bf16 v[108:111], v[172:175], v[198:201], v[108:111]
	v_mfma_f32_16x16x32_bf16 v[104:107], v[180:183], v[198:201], v[104:107]
	v_mfma_f32_16x16x32_bf16 v[92:95], v[172:175], v[206:209], v[92:95]
	v_mfma_f32_16x16x32_bf16 v[88:91], v[180:183], v[206:209], v[88:91]
	v_mfma_f32_16x16x32_bf16 v[76:79], v[172:175], v[214:217], v[76:79]
	v_mfma_f32_16x16x32_bf16 v[72:75], v[180:183], v[214:217], v[72:75]
	v_mfma_f32_16x16x32_bf16 v[124:127], v[176:179], v[194:197], v[124:127]
	v_mfma_f32_16x16x32_bf16 v[120:123], v[184:187], v[194:197], v[120:123]
	v_mfma_f32_16x16x32_bf16 v[108:111], v[176:179], v[202:205], v[108:111]
	v_mfma_f32_16x16x32_bf16 v[104:107], v[184:187], v[202:205], v[104:107]
	v_mfma_f32_16x16x32_bf16 v[92:95], v[176:179], v[210:213], v[92:95]
	v_mfma_f32_16x16x32_bf16 v[88:91], v[184:187], v[210:213], v[88:91]
	v_mfma_f32_16x16x32_bf16 v[76:79], v[176:179], v[218:221], v[76:79]
	v_mfma_f32_16x16x32_bf16 v[72:75], v[184:187], v[218:221], v[72:75]
	s_barrier
	s_add_i32 s49, s40, s26
	v_lshl_add_u64 v[146:147], s[22:23], 0, v[130:131]
	s_mov_b32 m0, s49
	ds_read_b128 v[190:193], v153 offset:16384
	ds_read_b128 v[194:197], v153 offset:17408
	ds_read_b128 v[198:201], v153 offset:18432
	ds_read_b128 v[202:205], v153 offset:19456
	ds_read_b128 v[206:209], v153 offset:20480
	ds_read_b128 v[210:213], v153 offset:21504
	ds_read_b128 v[214:217], v153 offset:22528
	ds_read_b128 v[218:221], v153 offset:23552
	global_load_lds_dwordx4 v[146:147], off
	s_add_i32 m0, s49, 0x2000
	s_add_u32 s50, s22, 0x80000
	v_lshl_add_u64 v[222:223], s[22:23], 0, v[134:135]
	s_addc_u32 s51, s23, 0
	s_add_i32 s49, s41, s26
	global_load_lds_dwordx4 v[222:223], off
	v_lshl_add_u64 v[224:225], s[50:51], 0, v[130:131]
	s_mov_b32 m0, s49
	v_lshl_add_u64 v[226:227], s[30:31], 0, v[132:133]
	global_load_lds_dwordx4 v[224:225], off
	v_lshl_add_u64 v[224:225], s[50:51], 0, v[134:135]
	s_add_i32 m0, s49, 0x2000
	s_nop 0
	global_load_lds_dwordx4 v[224:225], off
	v_lshl_add_u64 v[224:225], s[30:31], 0, v[128:129]
	s_mov_b32 m0, s11
	s_nop 0
	global_load_lds_dwordx4 v[224:225], off
	s_mov_b32 m0, s28
	s_nop 0
	global_load_lds_dwordx4 v[226:227], off
	s_waitcnt vmcnt(8)
	s_waitcnt lgkmcnt(0)
	s_barrier
	s_waitcnt lgkmcnt(0)
	v_mfma_f32_16x16x32_bf16 v[52:55], v[156:159], v[190:193], v[52:55]
	v_mfma_f32_16x16x32_bf16 v[48:51], v[164:167], v[190:193], v[48:51]
	v_mfma_f32_16x16x32_bf16 v[36:39], v[156:159], v[198:201], v[36:39]
	v_mfma_f32_16x16x32_bf16 v[32:35], v[164:167], v[198:201], v[32:35]
	v_mfma_f32_16x16x32_bf16 v[20:23], v[156:159], v[206:209], v[20:23]
	v_mfma_f32_16x16x32_bf16 v[16:19], v[164:167], v[206:209], v[16:19]
	v_mfma_f32_16x16x32_bf16 v[8:11], v[156:159], v[214:217], v[8:11]
	v_mfma_f32_16x16x32_bf16 v[0:3], v[164:167], v[214:217], v[0:3]
	v_mfma_f32_16x16x32_bf16 v[52:55], v[160:163], v[194:197], v[52:55]
	v_mfma_f32_16x16x32_bf16 v[48:51], v[168:171], v[194:197], v[48:51]
	v_mfma_f32_16x16x32_bf16 v[36:39], v[160:163], v[202:205], v[36:39]
	v_mfma_f32_16x16x32_bf16 v[32:35], v[168:171], v[202:205], v[32:35]
	v_mfma_f32_16x16x32_bf16 v[20:23], v[160:163], v[210:213], v[20:23]
	v_mfma_f32_16x16x32_bf16 v[16:19], v[168:171], v[210:213], v[16:19]
	v_mfma_f32_16x16x32_bf16 v[8:11], v[160:163], v[218:221], v[8:11]
	v_mfma_f32_16x16x32_bf16 v[0:3], v[168:171], v[218:221], v[0:3]
	v_mfma_f32_16x16x32_bf16 v[60:63], v[172:175], v[190:193], v[60:63]
	v_mfma_f32_16x16x32_bf16 v[56:59], v[180:183], v[190:193], v[56:59]
	v_mfma_f32_16x16x32_bf16 v[44:47], v[172:175], v[198:201], v[44:47]
	v_mfma_f32_16x16x32_bf16 v[40:43], v[180:183], v[198:201], v[40:43]
	v_mfma_f32_16x16x32_bf16 v[28:31], v[172:175], v[206:209], v[28:31]
	v_mfma_f32_16x16x32_bf16 v[24:27], v[180:183], v[206:209], v[24:27]
	v_mfma_f32_16x16x32_bf16 v[12:15], v[172:175], v[214:217], v[12:15]
	v_mfma_f32_16x16x32_bf16 v[4:7], v[180:183], v[214:217], v[4:7]
	v_mfma_f32_16x16x32_bf16 v[60:63], v[176:179], v[194:197], v[60:63]
	v_mfma_f32_16x16x32_bf16 v[56:59], v[184:187], v[194:197], v[56:59]
	v_mfma_f32_16x16x32_bf16 v[44:47], v[176:179], v[202:205], v[44:47]
	v_mfma_f32_16x16x32_bf16 v[40:43], v[184:187], v[202:205], v[40:43]
	v_mfma_f32_16x16x32_bf16 v[28:31], v[176:179], v[210:213], v[28:31]
	v_mfma_f32_16x16x32_bf16 v[24:27], v[184:187], v[210:213], v[24:27]
	v_mfma_f32_16x16x32_bf16 v[12:15], v[176:179], v[218:221], v[12:15]
	v_mfma_f32_16x16x32_bf16 v[4:7], v[184:187], v[218:221], v[4:7]
	s_barrier
	s_add_i32 s49, 0, 0x18000
	s_add_i32 s50, 0, 0x1c000
	v_add_u32_e32 v168, s49, v149
	v_add_u32_e32 v184, s50, v149
	ds_read_b128 v[156:159], v168
	ds_read_b128 v[160:163], v168 offset:1024
	ds_read_b128 v[164:167], v168 offset:2048
	ds_read_b128 v[168:171], v168 offset:3072
	ds_read_b128 v[172:175], v184
	ds_read_b128 v[176:179], v184 offset:1024
	ds_read_b128 v[180:183], v184 offset:2048
	ds_read_b128 v[184:187], v184 offset:3072
	s_add_u32 s30, s30, 0x80000
	s_addc_u32 s31, s31, 0
	s_mov_b32 m0, s29
	v_lshl_add_u64 v[228:229], s[30:31], 0, v[128:129]
	ds_read_b128 v[190:193], v153 offset:32768
	ds_read_b128 v[194:197], v153 offset:33792
	ds_read_b128 v[198:201], v153 offset:34816
	ds_read_b128 v[202:205], v153 offset:35840
	ds_read_b128 v[206:209], v153 offset:36864
	ds_read_b128 v[210:213], v153 offset:37888
	ds_read_b128 v[214:217], v153 offset:38912
	ds_read_b128 v[218:221], v153 offset:39936
	global_load_lds_dwordx4 v[228:229], off
	v_lshl_add_u64 v[228:229], s[30:31], 0, v[132:133]
	s_mov_b32 m0, s33
	s_nop 0
	global_load_lds_dwordx4 v[228:229], off
	s_waitcnt vmcnt(8)
	s_waitcnt lgkmcnt(0)
	s_barrier
	s_waitcnt lgkmcnt(0)
	v_mfma_f32_16x16x32_bf16 v[116:119], v[156:159], v[190:193], v[116:119]
	v_mfma_f32_16x16x32_bf16 v[112:115], v[164:167], v[190:193], v[112:115]
	v_mfma_f32_16x16x32_bf16 v[100:103], v[156:159], v[198:201], v[100:103]
	v_mfma_f32_16x16x32_bf16 v[96:99], v[164:167], v[198:201], v[96:99]
	v_mfma_f32_16x16x32_bf16 v[84:87], v[156:159], v[206:209], v[84:87]
	v_mfma_f32_16x16x32_bf16 v[80:83], v[164:167], v[206:209], v[80:83]
	v_mfma_f32_16x16x32_bf16 v[68:71], v[156:159], v[214:217], v[68:71]
	v_mfma_f32_16x16x32_bf16 v[64:67], v[164:167], v[214:217], v[64:67]
	v_mfma_f32_16x16x32_bf16 v[116:119], v[160:163], v[194:197], v[116:119]
	v_mfma_f32_16x16x32_bf16 v[112:115], v[168:171], v[194:197], v[112:115]
	v_mfma_f32_16x16x32_bf16 v[100:103], v[160:163], v[202:205], v[100:103]
	v_mfma_f32_16x16x32_bf16 v[96:99], v[168:171], v[202:205], v[96:99]
	v_mfma_f32_16x16x32_bf16 v[84:87], v[160:163], v[210:213], v[84:87]
	v_mfma_f32_16x16x32_bf16 v[80:83], v[168:171], v[210:213], v[80:83]
	v_mfma_f32_16x16x32_bf16 v[68:71], v[160:163], v[218:221], v[68:71]
	v_mfma_f32_16x16x32_bf16 v[64:67], v[168:171], v[218:221], v[64:67]
	v_mfma_f32_16x16x32_bf16 v[124:127], v[172:175], v[190:193], v[124:127]
	v_mfma_f32_16x16x32_bf16 v[120:123], v[180:183], v[190:193], v[120:123]
	v_mfma_f32_16x16x32_bf16 v[108:111], v[172:175], v[198:201], v[108:111]
	v_mfma_f32_16x16x32_bf16 v[104:107], v[180:183], v[198:201], v[104:107]
	v_mfma_f32_16x16x32_bf16 v[92:95], v[172:175], v[206:209], v[92:95]
	v_mfma_f32_16x16x32_bf16 v[88:91], v[180:183], v[206:209], v[88:91]
	v_mfma_f32_16x16x32_bf16 v[76:79], v[172:175], v[214:217], v[76:79]
	v_mfma_f32_16x16x32_bf16 v[72:75], v[180:183], v[214:217], v[72:75]
	v_mfma_f32_16x16x32_bf16 v[124:127], v[176:179], v[194:197], v[124:127]
	v_mfma_f32_16x16x32_bf16 v[120:123], v[184:187], v[194:197], v[120:123]
	v_mfma_f32_16x16x32_bf16 v[108:111], v[176:179], v[202:205], v[108:111]
	v_mfma_f32_16x16x32_bf16 v[104:107], v[184:187], v[202:205], v[104:107]
	v_mfma_f32_16x16x32_bf16 v[92:95], v[176:179], v[210:213], v[92:95]
	v_mfma_f32_16x16x32_bf16 v[88:91], v[184:187], v[210:213], v[88:91]
	v_mfma_f32_16x16x32_bf16 v[76:79], v[176:179], v[218:221], v[76:79]
	v_mfma_f32_16x16x32_bf16 v[72:75], v[184:187], v[218:221], v[72:75]
	s_barrier
	s_add_i32 s30, s49, s26
	v_lshl_add_u64 v[146:147], v[146:147], 0, s[6:7]
	s_mov_b32 m0, s30
	ds_read_b128 v[190:193], v153 offset:49152
	ds_read_b128 v[194:197], v153 offset:50176
	ds_read_b128 v[198:201], v153 offset:51200
	ds_read_b128 v[202:205], v153 offset:52224
	ds_read_b128 v[206:209], v153 offset:53248
	ds_read_b128 v[210:213], v153 offset:54272
	ds_read_b128 v[214:217], v153 offset:55296
	ds_read_b128 v[218:221], v153 offset:56320
	global_load_lds_dwordx4 v[146:147], off
	s_add_i32 m0, s30, 0x2000
	s_add_u32 s22, s22, 0x80080
	v_lshl_add_u64 v[146:147], v[222:223], 0, s[6:7]
	s_addc_u32 s23, s23, 0
	s_add_i32 s30, s50, s26
	global_load_lds_dwordx4 v[146:147], off
	v_lshl_add_u64 v[146:147], s[22:23], 0, v[130:131]
	s_mov_b32 m0, s30
	s_nop 0
	global_load_lds_dwordx4 v[146:147], off
	v_lshl_add_u64 v[146:147], s[22:23], 0, v[134:135]
	s_add_i32 m0, s30, 0x2000
	s_nop 0
	global_load_lds_dwordx4 v[146:147], off
	v_lshl_add_u64 v[146:147], v[224:225], 0, s[6:7]
	s_mov_b32 m0, s37
	s_nop 0
	global_load_lds_dwordx4 v[146:147], off
	v_lshl_add_u64 v[146:147], v[226:227], 0, s[6:7]
	s_mov_b32 m0, s38
	s_nop 0
	global_load_lds_dwordx4 v[146:147], off
	s_waitcnt vmcnt(8)
	s_waitcnt lgkmcnt(0)
	s_barrier
	s_waitcnt lgkmcnt(0)
	v_mfma_f32_16x16x32_bf16 v[52:55], v[156:159], v[190:193], v[52:55]
	v_mfma_f32_16x16x32_bf16 v[48:51], v[164:167], v[190:193], v[48:51]
	v_mfma_f32_16x16x32_bf16 v[36:39], v[156:159], v[198:201], v[36:39]
	v_mfma_f32_16x16x32_bf16 v[32:35], v[164:167], v[198:201], v[32:35]
	v_mfma_f32_16x16x32_bf16 v[20:23], v[156:159], v[206:209], v[20:23]
	v_mfma_f32_16x16x32_bf16 v[16:19], v[164:167], v[206:209], v[16:19]
	v_mfma_f32_16x16x32_bf16 v[8:11], v[156:159], v[214:217], v[8:11]
	v_mfma_f32_16x16x32_bf16 v[0:3], v[164:167], v[214:217], v[0:3]
	v_mfma_f32_16x16x32_bf16 v[52:55], v[160:163], v[194:197], v[52:55]
	v_mfma_f32_16x16x32_bf16 v[48:51], v[168:171], v[194:197], v[48:51]
	v_mfma_f32_16x16x32_bf16 v[36:39], v[160:163], v[202:205], v[36:39]
	v_mfma_f32_16x16x32_bf16 v[32:35], v[168:171], v[202:205], v[32:35]
	v_mfma_f32_16x16x32_bf16 v[20:23], v[160:163], v[210:213], v[20:23]
	v_mfma_f32_16x16x32_bf16 v[16:19], v[168:171], v[210:213], v[16:19]
	v_mfma_f32_16x16x32_bf16 v[8:11], v[160:163], v[218:221], v[8:11]
	v_mfma_f32_16x16x32_bf16 v[0:3], v[168:171], v[218:221], v[0:3]
	v_mfma_f32_16x16x32_bf16 v[60:63], v[172:175], v[190:193], v[60:63]
	v_mfma_f32_16x16x32_bf16 v[56:59], v[180:183], v[190:193], v[56:59]
	v_mfma_f32_16x16x32_bf16 v[44:47], v[172:175], v[198:201], v[44:47]
	v_mfma_f32_16x16x32_bf16 v[40:43], v[180:183], v[198:201], v[40:43]
	v_mfma_f32_16x16x32_bf16 v[28:31], v[172:175], v[206:209], v[28:31]
	v_mfma_f32_16x16x32_bf16 v[24:27], v[180:183], v[206:209], v[24:27]
	v_mfma_f32_16x16x32_bf16 v[12:15], v[172:175], v[214:217], v[12:15]
	v_mfma_f32_16x16x32_bf16 v[4:7], v[180:183], v[214:217], v[4:7]
	v_mfma_f32_16x16x32_bf16 v[60:63], v[176:179], v[194:197], v[60:63]
	v_mfma_f32_16x16x32_bf16 v[56:59], v[184:187], v[194:197], v[56:59]
	v_mfma_f32_16x16x32_bf16 v[44:47], v[176:179], v[202:205], v[44:47]
	v_mfma_f32_16x16x32_bf16 v[40:43], v[184:187], v[202:205], v[40:43]
	v_mfma_f32_16x16x32_bf16 v[28:31], v[176:179], v[210:213], v[28:31]
	v_mfma_f32_16x16x32_bf16 v[24:27], v[184:187], v[210:213], v[24:27]
	v_mfma_f32_16x16x32_bf16 v[12:15], v[176:179], v[218:221], v[12:15]
	v_mfma_f32_16x16x32_bf16 v[4:7], v[184:187], v[218:221], v[4:7]
	s_barrier
	s_add_i32 s48, s48, 2
	s_add_u32 s20, s20, 0x100
	s_addc_u32 s21, s21, 0
	s_add_u32 s46, s46, 0x100
	s_addc_u32 s47, s47, 0
	s_cmp_gt_u32 s48, 29
	s_cbranch_scc0 .LBB0_664
	s_and_b64 vcc, exec, s[8:9]
	s_cbranch_vccz .LBB0_667
	s_barrier

.LBB0_749:
	ds_read_b128 v[128:131], v179
	ds_read_b128 v[132:135], v179 offset:1024
	ds_read_b128 v[136:139], v179 offset:2048
	ds_read_b128 v[140:143], v179 offset:3072
	ds_read_b128 v[160:163], v180
	ds_read_b128 v[164:167], v180 offset:1024
	ds_read_b128 v[168:171], v180 offset:2048
	ds_read_b128 v[172:175], v180 offset:3072
	s_add_u32 s20, s10, 0xffea0080
	s_addc_u32 s21, s11, -1
	s_cmpk_eq_i32 s48, 0x54
	s_cselect_b32 s23, s1, s21
	s_cselect_b32 s22, s0, s20
	s_cselect_b32 s21, s19, s47
	s_cselect_b32 s20, s18, s46
	v_lshl_add_u64 v[218:219], s[10:11], 0, v[152:153]
	s_add_i32 m0, s27, 0xc000
	ds_read_b128 v[184:187], v181
	ds_read_b128 v[190:193], v181 offset:1024
	ds_read_b128 v[194:197], v181 offset:2048
	ds_read_b128 v[198:201], v181 offset:3072
	ds_read_b128 v[202:205], v181 offset:4096
	ds_read_b128 v[206:209], v181 offset:5120
	ds_read_b128 v[210:213], v181 offset:6144
	ds_read_b128 v[214:217], v181 offset:7168
	global_load_lds_dwordx4 v[218:219], off
	v_lshl_add_u64 v[218:219], s[10:11], 0, v[154:155]
	s_add_i32 m0, s27, 0xe000
	s_nop 0
	global_load_lds_dwordx4 v[218:219], off
	s_waitcnt vmcnt(8)
	s_waitcnt lgkmcnt(0)
	s_barrier
	s_waitcnt lgkmcnt(0)
	v_mfma_f32_16x16x32_bf16 v[124:127], v[128:131], v[184:187], v[124:127]
	v_mfma_f32_16x16x32_bf16 v[120:123], v[136:139], v[184:187], v[120:123]
	v_mfma_f32_16x16x32_bf16 v[108:111], v[128:131], v[194:197], v[108:111]
	v_mfma_f32_16x16x32_bf16 v[104:107], v[136:139], v[194:197], v[104:107]
	v_mfma_f32_16x16x32_bf16 v[92:95], v[128:131], v[202:205], v[92:95]
	v_mfma_f32_16x16x32_bf16 v[88:91], v[136:139], v[202:205], v[88:91]
	v_mfma_f32_16x16x32_bf16 v[76:79], v[128:131], v[210:213], v[76:79]
	v_mfma_f32_16x16x32_bf16 v[72:75], v[136:139], v[210:213], v[72:75]
	v_mfma_f32_16x16x32_bf16 v[124:127], v[132:135], v[190:193], v[124:127]
	v_mfma_f32_16x16x32_bf16 v[120:123], v[140:143], v[190:193], v[120:123]
	v_mfma_f32_16x16x32_bf16 v[108:111], v[132:135], v[198:201], v[108:111]
	v_mfma_f32_16x16x32_bf16 v[104:107], v[140:143], v[198:201], v[104:107]
	v_mfma_f32_16x16x32_bf16 v[92:95], v[132:135], v[206:209], v[92:95]
	v_mfma_f32_16x16x32_bf16 v[88:91], v[140:143], v[206:209], v[88:91]
	v_mfma_f32_16x16x32_bf16 v[76:79], v[132:135], v[214:217], v[76:79]
	v_mfma_f32_16x16x32_bf16 v[72:75], v[140:143], v[214:217], v[72:75]
	v_mfma_f32_16x16x32_bf16 v[116:119], v[160:163], v[184:187], v[116:119]
	v_mfma_f32_16x16x32_bf16 v[112:115], v[168:171], v[184:187], v[112:115]
	v_mfma_f32_16x16x32_bf16 v[100:103], v[160:163], v[194:197], v[100:103]
	v_mfma_f32_16x16x32_bf16 v[96:99], v[168:171], v[194:197], v[96:99]
	v_mfma_f32_16x16x32_bf16 v[84:87], v[160:163], v[202:205], v[84:87]
	v_mfma_f32_16x16x32_bf16 v[80:83], v[168:171], v[202:205], v[80:83]
	v_mfma_f32_16x16x32_bf16 v[68:71], v[160:163], v[210:213], v[68:71]
	v_mfma_f32_16x16x32_bf16 v[64:67], v[168:171], v[210:213], v[64:67]
	v_mfma_f32_16x16x32_bf16 v[116:119], v[164:167], v[190:193], v[116:119]
	v_mfma_f32_16x16x32_bf16 v[112:115], v[172:175], v[190:193], v[112:115]
	v_mfma_f32_16x16x32_bf16 v[100:103], v[164:167], v[198:201], v[100:103]
	v_mfma_f32_16x16x32_bf16 v[96:99], v[172:175], v[198:201], v[96:99]
	v_mfma_f32_16x16x32_bf16 v[84:87], v[164:167], v[206:209], v[84:87]
	v_mfma_f32_16x16x32_bf16 v[80:83], v[172:175], v[206:209], v[80:83]
	v_mfma_f32_16x16x32_bf16 v[68:71], v[164:167], v[214:217], v[68:71]
	v_mfma_f32_16x16x32_bf16 v[64:67], v[172:175], v[214:217], v[64:67]
	s_barrier
	s_add_i32 s49, s39, s26
	v_lshl_add_u64 v[218:219], s[20:21], 0, v[146:147]
	s_mov_b32 m0, s49
	ds_read_b128 v[184:187], v181 offset:16384
	ds_read_b128 v[190:193], v181 offset:17408
	ds_read_b128 v[194:197], v181 offset:18432
	ds_read_b128 v[198:201], v181 offset:19456
	ds_read_b128 v[202:205], v181 offset:20480
	ds_read_b128 v[206:209], v181 offset:21504
	ds_read_b128 v[210:213], v181 offset:22528
	ds_read_b128 v[214:217], v181 offset:23552
	global_load_lds_dwordx4 v[218:219], off
	s_add_i32 m0, s49, 0x2000
	s_add_u32 s50, s20, 0x160000
	v_lshl_add_u64 v[220:221], s[20:21], 0, v[150:151]
	s_addc_u32 s51, s21, 0
	s_add_i32 s49, s40, s26
	global_load_lds_dwordx4 v[220:221], off
	v_lshl_add_u64 v[222:223], s[50:51], 0, v[146:147]
	s_mov_b32 m0, s49
	v_lshl_add_u64 v[224:225], s[22:23], 0, v[148:149]
	global_load_lds_dwordx4 v[222:223], off
	v_lshl_add_u64 v[222:223], s[50:51], 0, v[150:151]
	s_add_i32 m0, s49, 0x2000
	s_nop 0
	global_load_lds_dwordx4 v[222:223], off
	v_lshl_add_u64 v[222:223], s[22:23], 0, v[144:145]
	s_mov_b32 m0, s27
	s_nop 0
	global_load_lds_dwordx4 v[222:223], off
	s_mov_b32 m0, s28
	s_nop 0
	global_load_lds_dwordx4 v[224:225], off
	s_waitcnt vmcnt(8)
	s_waitcnt lgkmcnt(0)
	s_barrier
	s_waitcnt lgkmcnt(0)
	v_mfma_f32_16x16x32_bf16 v[60:63], v[128:131], v[184:187], v[60:63]
	v_mfma_f32_16x16x32_bf16 v[56:59], v[136:139], v[184:187], v[56:59]
	v_mfma_f32_16x16x32_bf16 v[44:47], v[128:131], v[194:197], v[44:47]
	v_mfma_f32_16x16x32_bf16 v[40:43], v[136:139], v[194:197], v[40:43]
	v_mfma_f32_16x16x32_bf16 v[28:31], v[128:131], v[202:205], v[28:31]
	v_mfma_f32_16x16x32_bf16 v[24:27], v[136:139], v[202:205], v[24:27]
	v_mfma_f32_16x16x32_bf16 v[12:15], v[128:131], v[210:213], v[12:15]
	v_mfma_f32_16x16x32_bf16 v[8:11], v[136:139], v[210:213], v[8:11]
	v_mfma_f32_16x16x32_bf16 v[60:63], v[132:135], v[190:193], v[60:63]
	v_mfma_f32_16x16x32_bf16 v[56:59], v[140:143], v[190:193], v[56:59]
	v_mfma_f32_16x16x32_bf16 v[44:47], v[132:135], v[198:201], v[44:47]
	v_mfma_f32_16x16x32_bf16 v[40:43], v[140:143], v[198:201], v[40:43]
	v_mfma_f32_16x16x32_bf16 v[28:31], v[132:135], v[206:209], v[28:31]
	v_mfma_f32_16x16x32_bf16 v[24:27], v[140:143], v[206:209], v[24:27]
	v_mfma_f32_16x16x32_bf16 v[12:15], v[132:135], v[214:217], v[12:15]
	v_mfma_f32_16x16x32_bf16 v[8:11], v[140:143], v[214:217], v[8:11]
	v_mfma_f32_16x16x32_bf16 v[52:55], v[160:163], v[184:187], v[52:55]
	v_mfma_f32_16x16x32_bf16 v[48:51], v[168:171], v[184:187], v[48:51]
	v_mfma_f32_16x16x32_bf16 v[36:39], v[160:163], v[194:197], v[36:39]
	v_mfma_f32_16x16x32_bf16 v[32:35], v[168:171], v[194:197], v[32:35]
	v_mfma_f32_16x16x32_bf16 v[20:23], v[160:163], v[202:205], v[20:23]
	v_mfma_f32_16x16x32_bf16 v[16:19], v[168:171], v[202:205], v[16:19]
	v_mfma_f32_16x16x32_bf16 v[4:7], v[160:163], v[210:213], v[4:7]
	v_mfma_f32_16x16x32_bf16 v[0:3], v[168:171], v[210:213], v[0:3]
	v_mfma_f32_16x16x32_bf16 v[52:55], v[164:167], v[190:193], v[52:55]
	v_mfma_f32_16x16x32_bf16 v[48:51], v[172:175], v[190:193], v[48:51]
	v_mfma_f32_16x16x32_bf16 v[36:39], v[164:167], v[198:201], v[36:39]
	v_mfma_f32_16x16x32_bf16 v[32:35], v[172:175], v[198:201], v[32:35]
	v_mfma_f32_16x16x32_bf16 v[20:23], v[164:167], v[206:209], v[20:23]
	v_mfma_f32_16x16x32_bf16 v[16:19], v[172:175], v[206:209], v[16:19]
	v_mfma_f32_16x16x32_bf16 v[4:7], v[164:167], v[214:217], v[4:7]
	v_mfma_f32_16x16x32_bf16 v[0:3], v[172:175], v[214:217], v[0:3]
	s_barrier
	s_add_i32 s49, 0, 0x18000
	s_add_i32 s50, 0, 0x1c000
	v_add_u32_e32 v140, s49, v177
	v_add_u32_e32 v172, s50, v177
	ds_read_b128 v[128:131], v140
	ds_read_b128 v[132:135], v140 offset:1024
	ds_read_b128 v[136:139], v140 offset:2048
	ds_read_b128 v[140:143], v140 offset:3072
	ds_read_b128 v[160:163], v172
	ds_read_b128 v[164:167], v172 offset:1024
	ds_read_b128 v[168:171], v172 offset:2048
	ds_read_b128 v[172:175], v172 offset:3072
	s_add_u32 s22, s22, 0x160000
	s_addc_u32 s23, s23, 0
	s_mov_b32 m0, s29
	v_lshl_add_u64 v[226:227], s[22:23], 0, v[144:145]
	ds_read_b128 v[184:187], v181 offset:32768
	ds_read_b128 v[190:193], v181 offset:33792
	ds_read_b128 v[194:197], v181 offset:34816
	ds_read_b128 v[198:201], v181 offset:35840
	ds_read_b128 v[202:205], v181 offset:36864
	ds_read_b128 v[206:209], v181 offset:37888
	ds_read_b128 v[210:213], v181 offset:38912
	ds_read_b128 v[214:217], v181 offset:39936
	global_load_lds_dwordx4 v[226:227], off
	v_lshl_add_u64 v[226:227], s[22:23], 0, v[148:149]
	s_mov_b32 m0, s30
	s_nop 0
	global_load_lds_dwordx4 v[226:227], off
	s_waitcnt vmcnt(8)
	s_waitcnt lgkmcnt(0)
	s_barrier
	s_waitcnt lgkmcnt(0)
	v_mfma_f32_16x16x32_bf16 v[124:127], v[128:131], v[184:187], v[124:127]
	v_mfma_f32_16x16x32_bf16 v[120:123], v[136:139], v[184:187], v[120:123]
	v_mfma_f32_16x16x32_bf16 v[108:111], v[128:131], v[194:197], v[108:111]
	v_mfma_f32_16x16x32_bf16 v[104:107], v[136:139], v[194:197], v[104:107]
	v_mfma_f32_16x16x32_bf16 v[92:95], v[128:131], v[202:205], v[92:95]
	v_mfma_f32_16x16x32_bf16 v[88:91], v[136:139], v[202:205], v[88:91]
	v_mfma_f32_16x16x32_bf16 v[76:79], v[128:131], v[210:213], v[76:79]
	v_mfma_f32_16x16x32_bf16 v[72:75], v[136:139], v[210:213], v[72:75]
	v_mfma_f32_16x16x32_bf16 v[124:127], v[132:135], v[190:193], v[124:127]
	v_mfma_f32_16x16x32_bf16 v[120:123], v[140:143], v[190:193], v[120:123]
	v_mfma_f32_16x16x32_bf16 v[108:111], v[132:135], v[198:201], v[108:111]
	v_mfma_f32_16x16x32_bf16 v[104:107], v[140:143], v[198:201], v[104:107]
	v_mfma_f32_16x16x32_bf16 v[92:95], v[132:135], v[206:209], v[92:95]
	v_mfma_f32_16x16x32_bf16 v[88:91], v[140:143], v[206:209], v[88:91]
	v_mfma_f32_16x16x32_bf16 v[76:79], v[132:135], v[214:217], v[76:79]
	v_mfma_f32_16x16x32_bf16 v[72:75], v[140:143], v[214:217], v[72:75]
	v_mfma_f32_16x16x32_bf16 v[116:119], v[160:163], v[184:187], v[116:119]
	v_mfma_f32_16x16x32_bf16 v[112:115], v[168:171], v[184:187], v[112:115]
	v_mfma_f32_16x16x32_bf16 v[100:103], v[160:163], v[194:197], v[100:103]
	v_mfma_f32_16x16x32_bf16 v[96:99], v[168:171], v[194:197], v[96:99]
	v_mfma_f32_16x16x32_bf16 v[84:87], v[160:163], v[202:205], v[84:87]
	v_mfma_f32_16x16x32_bf16 v[80:83], v[168:171], v[202:205], v[80:83]
	v_mfma_f32_16x16x32_bf16 v[68:71], v[160:163], v[210:213], v[68:71]
	v_mfma_f32_16x16x32_bf16 v[64:67], v[168:171], v[210:213], v[64:67]
	v_mfma_f32_16x16x32_bf16 v[116:119], v[164:167], v[190:193], v[116:119]
	v_mfma_f32_16x16x32_bf16 v[112:115], v[172:175], v[190:193], v[112:115]
	v_mfma_f32_16x16x32_bf16 v[100:103], v[164:167], v[198:201], v[100:103]
	v_mfma_f32_16x16x32_bf16 v[96:99], v[172:175], v[198:201], v[96:99]
	v_mfma_f32_16x16x32_bf16 v[84:87], v[164:167], v[206:209], v[84:87]
	v_mfma_f32_16x16x32_bf16 v[80:83], v[172:175], v[206:209], v[80:83]
	v_mfma_f32_16x16x32_bf16 v[68:71], v[164:167], v[214:217], v[68:71]
	v_mfma_f32_16x16x32_bf16 v[64:67], v[172:175], v[214:217], v[64:67]
	s_barrier
	s_add_i32 s22, s49, s26
	v_lshl_add_u64 v[218:219], v[218:219], 0, s[12:13]
	s_mov_b32 m0, s22
	ds_read_b128 v[184:187], v181 offset:49152
	ds_read_b128 v[190:193], v181 offset:50176
	ds_read_b128 v[194:197], v181 offset:51200
	ds_read_b128 v[198:201], v181 offset:52224
	ds_read_b128 v[202:205], v181 offset:53248
	ds_read_b128 v[206:209], v181 offset:54272
	ds_read_b128 v[210:213], v181 offset:55296
	ds_read_b128 v[214:217], v181 offset:56320
	global_load_lds_dwordx4 v[218:219], off
	s_add_i32 m0, s22, 0x2000
	s_add_u32 s20, s20, 0x160080
	v_lshl_add_u64 v[218:219], v[220:221], 0, s[12:13]
	s_addc_u32 s21, s21, 0
	s_add_i32 s22, s50, s26
	global_load_lds_dwordx4 v[218:219], off
	v_lshl_add_u64 v[218:219], s[20:21], 0, v[146:147]
	s_mov_b32 m0, s22
	s_nop 0
	global_load_lds_dwordx4 v[218:219], off
	v_lshl_add_u64 v[218:219], s[20:21], 0, v[150:151]
	s_add_i32 m0, s22, 0x2000
	s_nop 0
	global_load_lds_dwordx4 v[218:219], off
	v_lshl_add_u64 v[218:219], v[222:223], 0, s[12:13]
	s_mov_b32 m0, s35
	s_nop 0
	global_load_lds_dwordx4 v[218:219], off
	v_lshl_add_u64 v[218:219], v[224:225], 0, s[12:13]
	s_mov_b32 m0, s36
	s_nop 0
	global_load_lds_dwordx4 v[218:219], off
	s_waitcnt vmcnt(8)
	s_waitcnt lgkmcnt(0)
	s_barrier
	s_waitcnt lgkmcnt(0)
	v_mfma_f32_16x16x32_bf16 v[60:63], v[128:131], v[184:187], v[60:63]
	v_mfma_f32_16x16x32_bf16 v[56:59], v[136:139], v[184:187], v[56:59]
	v_mfma_f32_16x16x32_bf16 v[44:47], v[128:131], v[194:197], v[44:47]
	v_mfma_f32_16x16x32_bf16 v[40:43], v[136:139], v[194:197], v[40:43]
	v_mfma_f32_16x16x32_bf16 v[28:31], v[128:131], v[202:205], v[28:31]
	v_mfma_f32_16x16x32_bf16 v[24:27], v[136:139], v[202:205], v[24:27]
	v_mfma_f32_16x16x32_bf16 v[12:15], v[128:131], v[210:213], v[12:15]
	v_mfma_f32_16x16x32_bf16 v[8:11], v[136:139], v[210:213], v[8:11]
	v_mfma_f32_16x16x32_bf16 v[60:63], v[132:135], v[190:193], v[60:63]
	v_mfma_f32_16x16x32_bf16 v[56:59], v[140:143], v[190:193], v[56:59]
	v_mfma_f32_16x16x32_bf16 v[44:47], v[132:135], v[198:201], v[44:47]
	v_mfma_f32_16x16x32_bf16 v[40:43], v[140:143], v[198:201], v[40:43]
	v_mfma_f32_16x16x32_bf16 v[28:31], v[132:135], v[206:209], v[28:31]
	v_mfma_f32_16x16x32_bf16 v[24:27], v[140:143], v[206:209], v[24:27]
	v_mfma_f32_16x16x32_bf16 v[12:15], v[132:135], v[214:217], v[12:15]
	v_mfma_f32_16x16x32_bf16 v[8:11], v[140:143], v[214:217], v[8:11]
	v_mfma_f32_16x16x32_bf16 v[52:55], v[160:163], v[184:187], v[52:55]
	v_mfma_f32_16x16x32_bf16 v[48:51], v[168:171], v[184:187], v[48:51]
	v_mfma_f32_16x16x32_bf16 v[36:39], v[160:163], v[194:197], v[36:39]
	v_mfma_f32_16x16x32_bf16 v[32:35], v[168:171], v[194:197], v[32:35]
	v_mfma_f32_16x16x32_bf16 v[20:23], v[160:163], v[202:205], v[20:23]
	v_mfma_f32_16x16x32_bf16 v[16:19], v[168:171], v[202:205], v[16:19]
	v_mfma_f32_16x16x32_bf16 v[4:7], v[160:163], v[210:213], v[4:7]
	v_mfma_f32_16x16x32_bf16 v[0:3], v[168:171], v[210:213], v[0:3]
	v_mfma_f32_16x16x32_bf16 v[52:55], v[164:167], v[190:193], v[52:55]
	v_mfma_f32_16x16x32_bf16 v[48:51], v[172:175], v[190:193], v[48:51]
	v_mfma_f32_16x16x32_bf16 v[36:39], v[164:167], v[198:201], v[36:39]
	v_mfma_f32_16x16x32_bf16 v[32:35], v[172:175], v[198:201], v[32:35]
	v_mfma_f32_16x16x32_bf16 v[20:23], v[164:167], v[206:209], v[20:23]
	v_mfma_f32_16x16x32_bf16 v[16:19], v[172:175], v[206:209], v[16:19]
	v_mfma_f32_16x16x32_bf16 v[4:7], v[164:167], v[214:217], v[4:7]
	v_mfma_f32_16x16x32_bf16 v[0:3], v[172:175], v[214:217], v[0:3]
	s_barrier
	s_add_i32 s48, s48, 2
	s_add_u32 s10, s10, 0x100
	s_addc_u32 s11, s11, 0
	s_add_u32 s46, s46, 0x100
	s_addc_u32 s47, s47, 0
	s_cmpk_gt_u32 s48, 0x55
	s_cbranch_scc0 .LBB0_749
	s_and_b64 vcc, exec, s[14:15]
	s_cbranch_vccz .LBB0_752
	s_barrier

.LBB0_838:
	ds_read_b128 v[154:157], v143
	ds_read_b128 v[164:167], v143 offset:1024
	ds_read_b128 v[168:171], v143 offset:2048
	ds_read_b128 v[172:175], v143 offset:3072
	ds_read_b128 v[176:179], v160
	ds_read_b128 v[180:183], v160 offset:1024
	ds_read_b128 v[184:187], v160 offset:2048
	ds_read_b128 v[190:193], v160 offset:3072
	s_add_u32 s44, s10, 0xfff80080
	s_addc_u32 s45, s11, -1
	s_cmp_eq_u32 s62, 28
	s_cselect_b32 s47, s7, s45
	s_cselect_b32 s46, s35, s44
	s_cselect_b32 s45, s37, s61
	s_cselect_b32 s44, s59, s60
	v_lshl_add_u64 v[226:227], s[10:11], 0, v[146:147]
	s_add_i32 m0, s27, 0xc000
	ds_read_b128 v[194:197], v161
	ds_read_b128 v[198:201], v161 offset:1024
	ds_read_b128 v[202:205], v161 offset:2048
	ds_read_b128 v[206:209], v161 offset:3072
	ds_read_b128 v[210:213], v161 offset:4096
	ds_read_b128 v[214:217], v161 offset:5120
	ds_read_b128 v[218:221], v161 offset:6144
	ds_read_b128 v[222:225], v161 offset:7168
	global_load_lds_dwordx4 v[226:227], off
	v_lshl_add_u64 v[226:227], s[10:11], 0, v[148:149]
	s_add_i32 m0, s27, 0xe000
	s_nop 0
	global_load_lds_dwordx4 v[226:227], off
	s_waitcnt vmcnt(8)
	s_waitcnt lgkmcnt(0)
	s_barrier
	s_waitcnt lgkmcnt(0)
	v_mfma_f32_16x16x32_bf16 v[124:127], v[154:157], v[194:197], v[124:127]
	v_mfma_f32_16x16x32_bf16 v[120:123], v[168:171], v[194:197], v[120:123]
	v_mfma_f32_16x16x32_bf16 v[108:111], v[154:157], v[202:205], v[108:111]
	v_mfma_f32_16x16x32_bf16 v[104:107], v[168:171], v[202:205], v[104:107]
	v_mfma_f32_16x16x32_bf16 v[92:95], v[154:157], v[210:213], v[92:95]
	v_mfma_f32_16x16x32_bf16 v[88:91], v[168:171], v[210:213], v[88:91]
	v_mfma_f32_16x16x32_bf16 v[76:79], v[154:157], v[218:221], v[76:79]
	v_mfma_f32_16x16x32_bf16 v[72:75], v[168:171], v[218:221], v[72:75]
	v_mfma_f32_16x16x32_bf16 v[124:127], v[164:167], v[198:201], v[124:127]
	v_mfma_f32_16x16x32_bf16 v[120:123], v[172:175], v[198:201], v[120:123]
	v_mfma_f32_16x16x32_bf16 v[108:111], v[164:167], v[206:209], v[108:111]
	v_mfma_f32_16x16x32_bf16 v[104:107], v[172:175], v[206:209], v[104:107]
	v_mfma_f32_16x16x32_bf16 v[92:95], v[164:167], v[214:217], v[92:95]
	v_mfma_f32_16x16x32_bf16 v[88:91], v[172:175], v[214:217], v[88:91]
	v_mfma_f32_16x16x32_bf16 v[76:79], v[164:167], v[222:225], v[76:79]
	v_mfma_f32_16x16x32_bf16 v[72:75], v[172:175], v[222:225], v[72:75]
	v_mfma_f32_16x16x32_bf16 v[116:119], v[176:179], v[194:197], v[116:119]
	v_mfma_f32_16x16x32_bf16 v[112:115], v[184:187], v[194:197], v[112:115]
	v_mfma_f32_16x16x32_bf16 v[100:103], v[176:179], v[202:205], v[100:103]
	v_mfma_f32_16x16x32_bf16 v[96:99], v[184:187], v[202:205], v[96:99]
	v_mfma_f32_16x16x32_bf16 v[84:87], v[176:179], v[210:213], v[84:87]
	v_mfma_f32_16x16x32_bf16 v[80:83], v[184:187], v[210:213], v[80:83]
	v_mfma_f32_16x16x32_bf16 v[68:71], v[176:179], v[218:221], v[68:71]
	v_mfma_f32_16x16x32_bf16 v[64:67], v[184:187], v[218:221], v[64:67]
	v_mfma_f32_16x16x32_bf16 v[116:119], v[180:183], v[198:201], v[116:119]
	v_mfma_f32_16x16x32_bf16 v[112:115], v[190:193], v[198:201], v[112:115]
	v_mfma_f32_16x16x32_bf16 v[100:103], v[180:183], v[206:209], v[100:103]
	v_mfma_f32_16x16x32_bf16 v[96:99], v[190:193], v[206:209], v[96:99]
	v_mfma_f32_16x16x32_bf16 v[84:87], v[180:183], v[214:217], v[84:87]
	v_mfma_f32_16x16x32_bf16 v[80:83], v[190:193], v[214:217], v[80:83]
	v_mfma_f32_16x16x32_bf16 v[68:71], v[180:183], v[222:225], v[68:71]
	v_mfma_f32_16x16x32_bf16 v[64:67], v[190:193], v[222:225], v[64:67]
	s_barrier
	s_add_i32 s63, s54, s26
	v_lshl_add_u64 v[226:227], s[44:45], 0, v[130:131]
	s_mov_b32 m0, s63
	ds_read_b128 v[194:197], v161 offset:16384
	ds_read_b128 v[198:201], v161 offset:17408
	ds_read_b128 v[202:205], v161 offset:18432
	ds_read_b128 v[206:209], v161 offset:19456
	ds_read_b128 v[210:213], v161 offset:20480
	ds_read_b128 v[214:217], v161 offset:21504
	ds_read_b128 v[218:221], v161 offset:22528
	ds_read_b128 v[222:225], v161 offset:23552
	global_load_lds_dwordx4 v[226:227], off
	s_add_i32 m0, s63, 0x2000
	s_add_u32 s64, s44, 0x80000
	v_lshl_add_u64 v[228:229], s[44:45], 0, v[134:135]
	s_addc_u32 s65, s45, 0
	s_add_i32 s63, s55, s26
	global_load_lds_dwordx4 v[228:229], off
	v_lshl_add_u64 v[230:231], s[64:65], 0, v[130:131]
	s_mov_b32 m0, s63
	v_lshl_add_u64 v[232:233], s[46:47], 0, v[132:133]
	global_load_lds_dwordx4 v[230:231], off
	v_lshl_add_u64 v[230:231], s[64:65], 0, v[134:135]
	s_add_i32 m0, s63, 0x2000
	s_nop 0
	global_load_lds_dwordx4 v[230:231], off
	v_lshl_add_u64 v[230:231], s[46:47], 0, v[128:129]
	s_mov_b32 m0, s27
	s_nop 0
	global_load_lds_dwordx4 v[230:231], off
	s_mov_b32 m0, s28
	s_nop 0
	global_load_lds_dwordx4 v[232:233], off
	s_waitcnt vmcnt(8)
	s_waitcnt lgkmcnt(0)
	s_barrier
	s_waitcnt lgkmcnt(0)
	v_mfma_f32_16x16x32_bf16 v[60:63], v[154:157], v[194:197], v[60:63]
	v_mfma_f32_16x16x32_bf16 v[56:59], v[168:171], v[194:197], v[56:59]
	v_mfma_f32_16x16x32_bf16 v[44:47], v[154:157], v[202:205], v[44:47]
	v_mfma_f32_16x16x32_bf16 v[40:43], v[168:171], v[202:205], v[40:43]
	v_mfma_f32_16x16x32_bf16 v[28:31], v[154:157], v[210:213], v[28:31]
	v_mfma_f32_16x16x32_bf16 v[24:27], v[168:171], v[210:213], v[24:27]
	v_mfma_f32_16x16x32_bf16 v[12:15], v[154:157], v[218:221], v[12:15]
	v_mfma_f32_16x16x32_bf16 v[8:11], v[168:171], v[218:221], v[8:11]
	v_mfma_f32_16x16x32_bf16 v[60:63], v[164:167], v[198:201], v[60:63]
	v_mfma_f32_16x16x32_bf16 v[56:59], v[172:175], v[198:201], v[56:59]
	v_mfma_f32_16x16x32_bf16 v[44:47], v[164:167], v[206:209], v[44:47]
	v_mfma_f32_16x16x32_bf16 v[40:43], v[172:175], v[206:209], v[40:43]
	v_mfma_f32_16x16x32_bf16 v[28:31], v[164:167], v[214:217], v[28:31]
	v_mfma_f32_16x16x32_bf16 v[24:27], v[172:175], v[214:217], v[24:27]
	v_mfma_f32_16x16x32_bf16 v[12:15], v[164:167], v[222:225], v[12:15]
	v_mfma_f32_16x16x32_bf16 v[8:11], v[172:175], v[222:225], v[8:11]
	v_mfma_f32_16x16x32_bf16 v[52:55], v[176:179], v[194:197], v[52:55]
	v_mfma_f32_16x16x32_bf16 v[48:51], v[184:187], v[194:197], v[48:51]
	v_mfma_f32_16x16x32_bf16 v[36:39], v[176:179], v[202:205], v[36:39]
	v_mfma_f32_16x16x32_bf16 v[32:35], v[184:187], v[202:205], v[32:35]
	v_mfma_f32_16x16x32_bf16 v[20:23], v[176:179], v[210:213], v[20:23]
	v_mfma_f32_16x16x32_bf16 v[16:19], v[184:187], v[210:213], v[16:19]
	v_mfma_f32_16x16x32_bf16 v[4:7], v[176:179], v[218:221], v[4:7]
	v_mfma_f32_16x16x32_bf16 v[0:3], v[184:187], v[218:221], v[0:3]
	v_mfma_f32_16x16x32_bf16 v[52:55], v[180:183], v[198:201], v[52:55]
	v_mfma_f32_16x16x32_bf16 v[48:51], v[190:193], v[198:201], v[48:51]
	v_mfma_f32_16x16x32_bf16 v[36:39], v[180:183], v[206:209], v[36:39]
	v_mfma_f32_16x16x32_bf16 v[32:35], v[190:193], v[206:209], v[32:35]
	v_mfma_f32_16x16x32_bf16 v[20:23], v[180:183], v[214:217], v[20:23]
	v_mfma_f32_16x16x32_bf16 v[16:19], v[190:193], v[214:217], v[16:19]
	v_mfma_f32_16x16x32_bf16 v[4:7], v[180:183], v[222:225], v[4:7]
	v_mfma_f32_16x16x32_bf16 v[0:3], v[190:193], v[222:225], v[0:3]
	s_barrier
	s_add_i32 s63, 0, 0x18000
	v_add_u32_e32 v136, s63, v159
	s_add_i32 s64, 0, 0x1c000
	ds_read_b128 v[154:157], v136
	ds_read_b128 v[164:167], v136 offset:1024
	ds_read_b128 v[168:171], v136 offset:2048
	ds_read_b128 v[172:175], v136 offset:3072
	v_add_u32_e32 v136, s64, v159
	ds_read_b128 v[176:179], v136
	ds_read_b128 v[180:183], v136 offset:1024
	ds_read_b128 v[184:187], v136 offset:2048
	ds_read_b128 v[190:193], v136 offset:3072
	s_add_u32 s46, s46, 0x80000
	s_addc_u32 s47, s47, 0
	s_mov_b32 m0, s29
	v_lshl_add_u64 v[234:235], s[46:47], 0, v[128:129]
	ds_read_b128 v[194:197], v161 offset:32768
	ds_read_b128 v[198:201], v161 offset:33792
	ds_read_b128 v[202:205], v161 offset:34816
	ds_read_b128 v[206:209], v161 offset:35840
	ds_read_b128 v[210:213], v161 offset:36864
	ds_read_b128 v[214:217], v161 offset:37888
	ds_read_b128 v[218:221], v161 offset:38912
	ds_read_b128 v[222:225], v161 offset:39936
	global_load_lds_dwordx4 v[234:235], off
	v_lshl_add_u64 v[234:235], s[46:47], 0, v[132:133]
	s_mov_b32 m0, s33
	s_nop 0
	global_load_lds_dwordx4 v[234:235], off
	s_waitcnt vmcnt(8)
	s_waitcnt lgkmcnt(0)
	s_barrier
	s_waitcnt lgkmcnt(0)
	v_mfma_f32_16x16x32_bf16 v[124:127], v[154:157], v[194:197], v[124:127]
	v_mfma_f32_16x16x32_bf16 v[120:123], v[168:171], v[194:197], v[120:123]
	v_mfma_f32_16x16x32_bf16 v[108:111], v[154:157], v[202:205], v[108:111]
	v_mfma_f32_16x16x32_bf16 v[104:107], v[168:171], v[202:205], v[104:107]
	v_mfma_f32_16x16x32_bf16 v[92:95], v[154:157], v[210:213], v[92:95]
	v_mfma_f32_16x16x32_bf16 v[88:91], v[168:171], v[210:213], v[88:91]
	v_mfma_f32_16x16x32_bf16 v[76:79], v[154:157], v[218:221], v[76:79]
	v_mfma_f32_16x16x32_bf16 v[72:75], v[168:171], v[218:221], v[72:75]
	v_mfma_f32_16x16x32_bf16 v[124:127], v[164:167], v[198:201], v[124:127]
	v_mfma_f32_16x16x32_bf16 v[120:123], v[172:175], v[198:201], v[120:123]
	v_mfma_f32_16x16x32_bf16 v[108:111], v[164:167], v[206:209], v[108:111]
	v_mfma_f32_16x16x32_bf16 v[104:107], v[172:175], v[206:209], v[104:107]
	v_mfma_f32_16x16x32_bf16 v[92:95], v[164:167], v[214:217], v[92:95]
	v_mfma_f32_16x16x32_bf16 v[88:91], v[172:175], v[214:217], v[88:91]
	v_mfma_f32_16x16x32_bf16 v[76:79], v[164:167], v[222:225], v[76:79]
	v_mfma_f32_16x16x32_bf16 v[72:75], v[172:175], v[222:225], v[72:75]
	v_mfma_f32_16x16x32_bf16 v[116:119], v[176:179], v[194:197], v[116:119]
	v_mfma_f32_16x16x32_bf16 v[112:115], v[184:187], v[194:197], v[112:115]
	v_mfma_f32_16x16x32_bf16 v[100:103], v[176:179], v[202:205], v[100:103]
	v_mfma_f32_16x16x32_bf16 v[96:99], v[184:187], v[202:205], v[96:99]
	v_mfma_f32_16x16x32_bf16 v[84:87], v[176:179], v[210:213], v[84:87]
	v_mfma_f32_16x16x32_bf16 v[80:83], v[184:187], v[210:213], v[80:83]
	v_mfma_f32_16x16x32_bf16 v[68:71], v[176:179], v[218:221], v[68:71]
	v_mfma_f32_16x16x32_bf16 v[64:67], v[184:187], v[218:221], v[64:67]
	v_mfma_f32_16x16x32_bf16 v[116:119], v[180:183], v[198:201], v[116:119]
	v_mfma_f32_16x16x32_bf16 v[112:115], v[190:193], v[198:201], v[112:115]
	v_mfma_f32_16x16x32_bf16 v[100:103], v[180:183], v[206:209], v[100:103]
	v_mfma_f32_16x16x32_bf16 v[96:99], v[190:193], v[206:209], v[96:99]
	v_mfma_f32_16x16x32_bf16 v[84:87], v[180:183], v[214:217], v[84:87]
	v_mfma_f32_16x16x32_bf16 v[80:83], v[190:193], v[214:217], v[80:83]
	v_mfma_f32_16x16x32_bf16 v[68:71], v[180:183], v[222:225], v[68:71]
	v_mfma_f32_16x16x32_bf16 v[64:67], v[190:193], v[222:225], v[64:67]
	s_barrier
	s_add_i32 s46, s63, s26
	v_lshl_add_u64 v[226:227], v[226:227], 0, s[18:19]
	s_mov_b32 m0, s46
	ds_read_b128 v[194:197], v161 offset:49152
	ds_read_b128 v[198:201], v161 offset:50176
	ds_read_b128 v[202:205], v161 offset:51200
	ds_read_b128 v[206:209], v161 offset:52224
	ds_read_b128 v[210:213], v161 offset:53248
	ds_read_b128 v[214:217], v161 offset:54272
	ds_read_b128 v[218:221], v161 offset:55296
	ds_read_b128 v[222:225], v161 offset:56320
	global_load_lds_dwordx4 v[226:227], off
	s_add_i32 m0, s46, 0x2000
	s_add_u32 s44, s44, 0x80080
	v_lshl_add_u64 v[226:227], v[228:229], 0, s[18:19]
	s_addc_u32 s45, s45, 0
	s_add_i32 s46, s64, s26
	global_load_lds_dwordx4 v[226:227], off
	v_lshl_add_u64 v[226:227], s[44:45], 0, v[130:131]
	s_mov_b32 m0, s46
	s_nop 0
	global_load_lds_dwordx4 v[226:227], off
	v_lshl_add_u64 v[226:227], s[44:45], 0, v[134:135]
	s_add_i32 m0, s46, 0x2000
	s_nop 0
	global_load_lds_dwordx4 v[226:227], off
	v_lshl_add_u64 v[226:227], v[230:231], 0, s[18:19]
	s_mov_b32 m0, s50
	s_nop 0
	global_load_lds_dwordx4 v[226:227], off
	v_lshl_add_u64 v[226:227], v[232:233], 0, s[18:19]
	s_mov_b32 m0, s51
	s_nop 0
	global_load_lds_dwordx4 v[226:227], off
	s_waitcnt vmcnt(8)
	s_waitcnt lgkmcnt(0)
	s_barrier
	s_waitcnt lgkmcnt(0)
	v_mfma_f32_16x16x32_bf16 v[60:63], v[154:157], v[194:197], v[60:63]
	v_mfma_f32_16x16x32_bf16 v[56:59], v[168:171], v[194:197], v[56:59]
	v_mfma_f32_16x16x32_bf16 v[44:47], v[154:157], v[202:205], v[44:47]
	v_mfma_f32_16x16x32_bf16 v[40:43], v[168:171], v[202:205], v[40:43]
	v_mfma_f32_16x16x32_bf16 v[28:31], v[154:157], v[210:213], v[28:31]
	v_mfma_f32_16x16x32_bf16 v[24:27], v[168:171], v[210:213], v[24:27]
	v_mfma_f32_16x16x32_bf16 v[12:15], v[154:157], v[218:221], v[12:15]
	v_mfma_f32_16x16x32_bf16 v[8:11], v[168:171], v[218:221], v[8:11]
	v_mfma_f32_16x16x32_bf16 v[60:63], v[164:167], v[198:201], v[60:63]
	v_mfma_f32_16x16x32_bf16 v[56:59], v[172:175], v[198:201], v[56:59]
	v_mfma_f32_16x16x32_bf16 v[44:47], v[164:167], v[206:209], v[44:47]
	v_mfma_f32_16x16x32_bf16 v[40:43], v[172:175], v[206:209], v[40:43]
	v_mfma_f32_16x16x32_bf16 v[28:31], v[164:167], v[214:217], v[28:31]
	v_mfma_f32_16x16x32_bf16 v[24:27], v[172:175], v[214:217], v[24:27]
	v_mfma_f32_16x16x32_bf16 v[12:15], v[164:167], v[222:225], v[12:15]
	v_mfma_f32_16x16x32_bf16 v[8:11], v[172:175], v[222:225], v[8:11]
	v_mfma_f32_16x16x32_bf16 v[52:55], v[176:179], v[194:197], v[52:55]
	v_mfma_f32_16x16x32_bf16 v[48:51], v[184:187], v[194:197], v[48:51]
	v_mfma_f32_16x16x32_bf16 v[36:39], v[176:179], v[202:205], v[36:39]
	v_mfma_f32_16x16x32_bf16 v[32:35], v[184:187], v[202:205], v[32:35]
	v_mfma_f32_16x16x32_bf16 v[20:23], v[176:179], v[210:213], v[20:23]
	v_mfma_f32_16x16x32_bf16 v[16:19], v[184:187], v[210:213], v[16:19]
	v_mfma_f32_16x16x32_bf16 v[4:7], v[176:179], v[218:221], v[4:7]
	v_mfma_f32_16x16x32_bf16 v[0:3], v[184:187], v[218:221], v[0:3]
	v_mfma_f32_16x16x32_bf16 v[52:55], v[180:183], v[198:201], v[52:55]
	v_mfma_f32_16x16x32_bf16 v[48:51], v[190:193], v[198:201], v[48:51]
	v_mfma_f32_16x16x32_bf16 v[36:39], v[180:183], v[206:209], v[36:39]
	v_mfma_f32_16x16x32_bf16 v[32:35], v[190:193], v[206:209], v[32:35]
	v_mfma_f32_16x16x32_bf16 v[20:23], v[180:183], v[214:217], v[20:23]
	v_mfma_f32_16x16x32_bf16 v[16:19], v[190:193], v[214:217], v[16:19]
	v_mfma_f32_16x16x32_bf16 v[4:7], v[180:183], v[222:225], v[4:7]
	v_mfma_f32_16x16x32_bf16 v[0:3], v[190:193], v[222:225], v[0:3]
	s_barrier
	s_add_i32 s62, s62, 2
	s_add_u32 s10, s10, 0x100
	s_addc_u32 s11, s11, 0
	s_add_u32 s60, s60, 0x100
	s_addc_u32 s61, s61, 0
	s_cmp_gt_u32 s62, 29
	s_cbranch_scc0 .LBB0_838
	s_and_b64 vcc, exec, s[20:21]
	s_cbranch_vccnz .LBB0_843
	v_lshl_add_u32 v154, s6, 8, v158
	s_cmp_gt_i32 s42, 3
	s_mov_b64 s[6:7], -1
	s_cbranch_scc1 .LBB0_844

.LBB0_947:
	ds_read_b128 v[154:157], v137
	ds_read_b128 v[158:161], v137 offset:1024
	ds_read_b128 v[174:177], v137 offset:2048
	ds_read_b128 v[178:181], v137 offset:3072
	ds_read_b128 v[182:185], v170
	ds_read_b128 v[190:193], v170 offset:1024
	ds_read_b128 v[194:197], v170 offset:2048
	ds_read_b128 v[198:201], v170 offset:3072
	s_add_u32 s34, s10, 0xfffe0080
	s_addc_u32 s35, s11, -1
	s_cmp_eq_u32 s53, 4
	s_cselect_b32 s37, s5, s35
	s_cselect_b32 s36, s9, s34
	s_cselect_b32 s35, s13, s52
	s_cselect_b32 s34, s16, s51
	v_lshl_add_u64 v[186:187], s[10:11], 0, v[146:147]
	s_add_i32 m0, s15, 0xc000
	ds_read_b128 v[202:205], v171
	ds_read_b128 v[206:209], v171 offset:1024
	ds_read_b128 v[210:213], v171 offset:2048
	ds_read_b128 v[214:217], v171 offset:3072
	ds_read_b128 v[218:221], v171 offset:4096
	ds_read_b128 v[222:225], v171 offset:5120
	ds_read_b128 v[226:229], v171 offset:6144
	ds_read_b128 v[230:233], v171 offset:7168
	global_load_lds_dwordx4 v[186:187], off
	v_lshl_add_u64 v[186:187], s[10:11], 0, v[148:149]
	s_add_i32 m0, s15, 0xe000
	s_nop 0
	global_load_lds_dwordx4 v[186:187], off
	s_waitcnt vmcnt(8)
	s_waitcnt lgkmcnt(0)
	s_barrier
	s_waitcnt lgkmcnt(0)
	v_mfma_f32_16x16x32_bf16 v[124:127], v[154:157], v[202:205], v[124:127]
	v_mfma_f32_16x16x32_bf16 v[120:123], v[174:177], v[202:205], v[120:123]
	v_mfma_f32_16x16x32_bf16 v[108:111], v[154:157], v[210:213], v[108:111]
	v_mfma_f32_16x16x32_bf16 v[104:107], v[174:177], v[210:213], v[104:107]
	v_mfma_f32_16x16x32_bf16 v[92:95], v[154:157], v[218:221], v[92:95]
	v_mfma_f32_16x16x32_bf16 v[88:91], v[174:177], v[218:221], v[88:91]
	v_mfma_f32_16x16x32_bf16 v[76:79], v[154:157], v[226:229], v[76:79]
	v_mfma_f32_16x16x32_bf16 v[72:75], v[174:177], v[226:229], v[72:75]
	v_mfma_f32_16x16x32_bf16 v[124:127], v[158:161], v[206:209], v[124:127]
	v_mfma_f32_16x16x32_bf16 v[120:123], v[178:181], v[206:209], v[120:123]
	v_mfma_f32_16x16x32_bf16 v[108:111], v[158:161], v[214:217], v[108:111]
	v_mfma_f32_16x16x32_bf16 v[104:107], v[178:181], v[214:217], v[104:107]
	v_mfma_f32_16x16x32_bf16 v[92:95], v[158:161], v[222:225], v[92:95]
	v_mfma_f32_16x16x32_bf16 v[88:91], v[178:181], v[222:225], v[88:91]
	v_mfma_f32_16x16x32_bf16 v[76:79], v[158:161], v[230:233], v[76:79]
	v_mfma_f32_16x16x32_bf16 v[72:75], v[178:181], v[230:233], v[72:75]
	v_mfma_f32_16x16x32_bf16 v[116:119], v[182:185], v[202:205], v[116:119]
	v_mfma_f32_16x16x32_bf16 v[112:115], v[194:197], v[202:205], v[112:115]
	v_mfma_f32_16x16x32_bf16 v[100:103], v[182:185], v[210:213], v[100:103]
	v_mfma_f32_16x16x32_bf16 v[96:99], v[194:197], v[210:213], v[96:99]
	v_mfma_f32_16x16x32_bf16 v[84:87], v[182:185], v[218:221], v[84:87]
	v_mfma_f32_16x16x32_bf16 v[80:83], v[194:197], v[218:221], v[80:83]
	v_mfma_f32_16x16x32_bf16 v[68:71], v[182:185], v[226:229], v[68:71]
	v_mfma_f32_16x16x32_bf16 v[64:67], v[194:197], v[226:229], v[64:67]
	v_mfma_f32_16x16x32_bf16 v[116:119], v[190:193], v[206:209], v[116:119]
	v_mfma_f32_16x16x32_bf16 v[112:115], v[198:201], v[206:209], v[112:115]
	v_mfma_f32_16x16x32_bf16 v[100:103], v[190:193], v[214:217], v[100:103]
	v_mfma_f32_16x16x32_bf16 v[96:99], v[198:201], v[214:217], v[96:99]
	v_mfma_f32_16x16x32_bf16 v[84:87], v[190:193], v[222:225], v[84:87]
	v_mfma_f32_16x16x32_bf16 v[80:83], v[198:201], v[222:225], v[80:83]
	v_mfma_f32_16x16x32_bf16 v[68:71], v[190:193], v[230:233], v[68:71]
	v_mfma_f32_16x16x32_bf16 v[64:67], v[198:201], v[230:233], v[64:67]
	s_barrier
	s_add_i32 s54, s47, s26
	v_lshl_add_u64 v[186:187], s[34:35], 0, v[130:131]
	s_mov_b32 m0, s54
	ds_read_b128 v[202:205], v171 offset:16384
	ds_read_b128 v[206:209], v171 offset:17408
	ds_read_b128 v[210:213], v171 offset:18432
	ds_read_b128 v[214:217], v171 offset:19456
	ds_read_b128 v[218:221], v171 offset:20480
	ds_read_b128 v[222:225], v171 offset:21504
	ds_read_b128 v[226:229], v171 offset:22528
	ds_read_b128 v[230:233], v171 offset:23552
	global_load_lds_dwordx4 v[186:187], off
	s_add_i32 m0, s54, 0x2000
	s_add_u32 s54, s34, 0x20000
	v_lshl_add_u64 v[234:235], s[34:35], 0, v[134:135]
	s_addc_u32 s55, s35, 0
	s_add_i32 s58, s48, s26
	global_load_lds_dwordx4 v[234:235], off
	v_lshl_add_u64 v[236:237], s[54:55], 0, v[130:131]
	s_mov_b32 m0, s58
	v_lshl_add_u64 v[238:239], s[36:37], 0, v[132:133]
	global_load_lds_dwordx4 v[236:237], off
	v_lshl_add_u64 v[236:237], s[54:55], 0, v[134:135]
	s_add_i32 m0, s58, 0x2000
	s_nop 0
	global_load_lds_dwordx4 v[236:237], off
	v_lshl_add_u64 v[236:237], s[36:37], 0, v[128:129]
	s_mov_b32 m0, s15
	s_nop 0
	global_load_lds_dwordx4 v[236:237], off
	s_mov_b32 m0, s27
	s_nop 0
	global_load_lds_dwordx4 v[238:239], off
	s_waitcnt vmcnt(8)
	s_waitcnt lgkmcnt(0)
	s_barrier
	s_waitcnt lgkmcnt(0)
	v_mfma_f32_16x16x32_bf16 v[60:63], v[154:157], v[202:205], v[60:63]
	v_mfma_f32_16x16x32_bf16 v[56:59], v[174:177], v[202:205], v[56:59]
	v_mfma_f32_16x16x32_bf16 v[44:47], v[154:157], v[210:213], v[44:47]
	v_mfma_f32_16x16x32_bf16 v[40:43], v[174:177], v[210:213], v[40:43]
	v_mfma_f32_16x16x32_bf16 v[28:31], v[154:157], v[218:221], v[28:31]
	v_mfma_f32_16x16x32_bf16 v[24:27], v[174:177], v[218:221], v[24:27]
	v_mfma_f32_16x16x32_bf16 v[12:15], v[154:157], v[226:229], v[12:15]
	v_mfma_f32_16x16x32_bf16 v[8:11], v[174:177], v[226:229], v[8:11]
	v_mfma_f32_16x16x32_bf16 v[60:63], v[158:161], v[206:209], v[60:63]
	v_mfma_f32_16x16x32_bf16 v[56:59], v[178:181], v[206:209], v[56:59]
	v_mfma_f32_16x16x32_bf16 v[44:47], v[158:161], v[214:217], v[44:47]
	v_mfma_f32_16x16x32_bf16 v[40:43], v[178:181], v[214:217], v[40:43]
	v_mfma_f32_16x16x32_bf16 v[28:31], v[158:161], v[222:225], v[28:31]
	v_mfma_f32_16x16x32_bf16 v[24:27], v[178:181], v[222:225], v[24:27]
	v_mfma_f32_16x16x32_bf16 v[12:15], v[158:161], v[230:233], v[12:15]
	v_mfma_f32_16x16x32_bf16 v[8:11], v[178:181], v[230:233], v[8:11]
	v_mfma_f32_16x16x32_bf16 v[52:55], v[182:185], v[202:205], v[52:55]
	v_mfma_f32_16x16x32_bf16 v[48:51], v[194:197], v[202:205], v[48:51]
	v_mfma_f32_16x16x32_bf16 v[36:39], v[182:185], v[210:213], v[36:39]
	v_mfma_f32_16x16x32_bf16 v[32:35], v[194:197], v[210:213], v[32:35]
	v_mfma_f32_16x16x32_bf16 v[20:23], v[182:185], v[218:221], v[20:23]
	v_mfma_f32_16x16x32_bf16 v[16:19], v[194:197], v[218:221], v[16:19]
	v_mfma_f32_16x16x32_bf16 v[4:7], v[182:185], v[226:229], v[4:7]
	v_mfma_f32_16x16x32_bf16 v[0:3], v[194:197], v[226:229], v[0:3]
	v_mfma_f32_16x16x32_bf16 v[52:55], v[190:193], v[206:209], v[52:55]
	v_mfma_f32_16x16x32_bf16 v[48:51], v[198:201], v[206:209], v[48:51]
	v_mfma_f32_16x16x32_bf16 v[36:39], v[190:193], v[214:217], v[36:39]
	v_mfma_f32_16x16x32_bf16 v[32:35], v[198:201], v[214:217], v[32:35]
	v_mfma_f32_16x16x32_bf16 v[20:23], v[190:193], v[222:225], v[20:23]
	v_mfma_f32_16x16x32_bf16 v[16:19], v[198:201], v[222:225], v[16:19]
	v_mfma_f32_16x16x32_bf16 v[4:7], v[190:193], v[230:233], v[4:7]
	v_mfma_f32_16x16x32_bf16 v[0:3], v[198:201], v[230:233], v[0:3]
	s_barrier
	s_add_i32 s54, 0, 0x18000
	v_add_u32_e32 v138, s54, v169
	s_add_i32 s55, 0, 0x1c000
	ds_read_b128 v[154:157], v138
	ds_read_b128 v[158:161], v138 offset:1024
	ds_read_b128 v[174:177], v138 offset:2048
	ds_read_b128 v[178:181], v138 offset:3072
	v_add_u32_e32 v138, s55, v169
	ds_read_b128 v[182:185], v138
	ds_read_b128 v[190:193], v138 offset:1024
	ds_read_b128 v[194:197], v138 offset:2048
	ds_read_b128 v[198:201], v138 offset:3072
	s_add_u32 s36, s36, 0x20000
	s_addc_u32 s37, s37, 0
	s_mov_b32 m0, s38
	v_lshl_add_u64 v[240:241], s[36:37], 0, v[128:129]
	ds_read_b128 v[202:205], v171 offset:32768
	ds_read_b128 v[206:209], v171 offset:33792
	ds_read_b128 v[210:213], v171 offset:34816
	ds_read_b128 v[214:217], v171 offset:35840
	ds_read_b128 v[218:221], v171 offset:36864
	ds_read_b128 v[222:225], v171 offset:37888
	ds_read_b128 v[226:229], v171 offset:38912
	ds_read_b128 v[230:233], v171 offset:39936
	global_load_lds_dwordx4 v[240:241], off
	v_lshl_add_u64 v[240:241], s[36:37], 0, v[132:133]
	s_mov_b32 m0, s39
	s_nop 0
	global_load_lds_dwordx4 v[240:241], off
	s_waitcnt vmcnt(8)
	s_waitcnt lgkmcnt(0)
	s_barrier
	s_waitcnt lgkmcnt(0)
	v_mfma_f32_16x16x32_bf16 v[124:127], v[154:157], v[202:205], v[124:127]
	v_mfma_f32_16x16x32_bf16 v[120:123], v[174:177], v[202:205], v[120:123]
	v_mfma_f32_16x16x32_bf16 v[108:111], v[154:157], v[210:213], v[108:111]
	v_mfma_f32_16x16x32_bf16 v[104:107], v[174:177], v[210:213], v[104:107]
	v_mfma_f32_16x16x32_bf16 v[92:95], v[154:157], v[218:221], v[92:95]
	v_mfma_f32_16x16x32_bf16 v[88:91], v[174:177], v[218:221], v[88:91]
	v_mfma_f32_16x16x32_bf16 v[76:79], v[154:157], v[226:229], v[76:79]
	v_mfma_f32_16x16x32_bf16 v[72:75], v[174:177], v[226:229], v[72:75]
	v_mfma_f32_16x16x32_bf16 v[124:127], v[158:161], v[206:209], v[124:127]
	v_mfma_f32_16x16x32_bf16 v[120:123], v[178:181], v[206:209], v[120:123]
	v_mfma_f32_16x16x32_bf16 v[108:111], v[158:161], v[214:217], v[108:111]
	v_mfma_f32_16x16x32_bf16 v[104:107], v[178:181], v[214:217], v[104:107]
	v_mfma_f32_16x16x32_bf16 v[92:95], v[158:161], v[222:225], v[92:95]
	v_mfma_f32_16x16x32_bf16 v[88:91], v[178:181], v[222:225], v[88:91]
	v_mfma_f32_16x16x32_bf16 v[76:79], v[158:161], v[230:233], v[76:79]
	v_mfma_f32_16x16x32_bf16 v[72:75], v[178:181], v[230:233], v[72:75]
	v_mfma_f32_16x16x32_bf16 v[116:119], v[182:185], v[202:205], v[116:119]
	v_mfma_f32_16x16x32_bf16 v[112:115], v[194:197], v[202:205], v[112:115]
	v_mfma_f32_16x16x32_bf16 v[100:103], v[182:185], v[210:213], v[100:103]
	v_mfma_f32_16x16x32_bf16 v[96:99], v[194:197], v[210:213], v[96:99]
	v_mfma_f32_16x16x32_bf16 v[84:87], v[182:185], v[218:221], v[84:87]
	v_mfma_f32_16x16x32_bf16 v[80:83], v[194:197], v[218:221], v[80:83]
	v_mfma_f32_16x16x32_bf16 v[68:71], v[182:185], v[226:229], v[68:71]
	v_mfma_f32_16x16x32_bf16 v[64:67], v[194:197], v[226:229], v[64:67]
	v_mfma_f32_16x16x32_bf16 v[116:119], v[190:193], v[206:209], v[116:119]
	v_mfma_f32_16x16x32_bf16 v[112:115], v[198:201], v[206:209], v[112:115]
	v_mfma_f32_16x16x32_bf16 v[100:103], v[190:193], v[214:217], v[100:103]
	v_mfma_f32_16x16x32_bf16 v[96:99], v[198:201], v[214:217], v[96:99]
	v_mfma_f32_16x16x32_bf16 v[84:87], v[190:193], v[222:225], v[84:87]
	v_mfma_f32_16x16x32_bf16 v[80:83], v[198:201], v[222:225], v[80:83]
	v_mfma_f32_16x16x32_bf16 v[68:71], v[190:193], v[230:233], v[68:71]
	v_mfma_f32_16x16x32_bf16 v[64:67], v[198:201], v[230:233], v[64:67]
	s_barrier
	s_add_i32 s36, s54, s26
	v_lshl_add_u64 v[186:187], v[186:187], 0, s[20:21]
	s_mov_b32 m0, s36
	ds_read_b128 v[202:205], v171 offset:49152
	ds_read_b128 v[206:209], v171 offset:50176
	ds_read_b128 v[210:213], v171 offset:51200
	ds_read_b128 v[214:217], v171 offset:52224
	ds_read_b128 v[218:221], v171 offset:53248
	ds_read_b128 v[222:225], v171 offset:54272
	ds_read_b128 v[226:229], v171 offset:55296
	ds_read_b128 v[230:233], v171 offset:56320
	global_load_lds_dwordx4 v[186:187], off
	s_add_i32 m0, s36, 0x2000
	s_add_u32 s34, s34, 0x20080
	v_lshl_add_u64 v[186:187], v[234:235], 0, s[20:21]
	s_addc_u32 s35, s35, 0
	s_add_i32 s36, s55, s26
	global_load_lds_dwordx4 v[186:187], off
	v_lshl_add_u64 v[186:187], s[34:35], 0, v[130:131]
	s_mov_b32 m0, s36
	s_nop 0
	global_load_lds_dwordx4 v[186:187], off
	v_lshl_add_u64 v[186:187], s[34:35], 0, v[134:135]
	s_add_i32 m0, s36, 0x2000
	s_nop 0
	global_load_lds_dwordx4 v[186:187], off
	v_lshl_add_u64 v[186:187], v[236:237], 0, s[20:21]
	s_mov_b32 m0, s41
	s_nop 0
	global_load_lds_dwordx4 v[186:187], off
	v_lshl_add_u64 v[186:187], v[238:239], 0, s[20:21]
	s_mov_b32 m0, s42
	s_nop 0
	global_load_lds_dwordx4 v[186:187], off
	s_waitcnt vmcnt(8)
	s_waitcnt lgkmcnt(0)
	s_barrier
	s_waitcnt lgkmcnt(0)
	v_mfma_f32_16x16x32_bf16 v[60:63], v[154:157], v[202:205], v[60:63]
	v_mfma_f32_16x16x32_bf16 v[56:59], v[174:177], v[202:205], v[56:59]
	v_mfma_f32_16x16x32_bf16 v[44:47], v[154:157], v[210:213], v[44:47]
	v_mfma_f32_16x16x32_bf16 v[40:43], v[174:177], v[210:213], v[40:43]
	v_mfma_f32_16x16x32_bf16 v[28:31], v[154:157], v[218:221], v[28:31]
	v_mfma_f32_16x16x32_bf16 v[24:27], v[174:177], v[218:221], v[24:27]
	v_mfma_f32_16x16x32_bf16 v[12:15], v[154:157], v[226:229], v[12:15]
	v_mfma_f32_16x16x32_bf16 v[8:11], v[174:177], v[226:229], v[8:11]
	v_mfma_f32_16x16x32_bf16 v[60:63], v[158:161], v[206:209], v[60:63]
	v_mfma_f32_16x16x32_bf16 v[56:59], v[178:181], v[206:209], v[56:59]
	v_mfma_f32_16x16x32_bf16 v[44:47], v[158:161], v[214:217], v[44:47]
	v_mfma_f32_16x16x32_bf16 v[40:43], v[178:181], v[214:217], v[40:43]
	v_mfma_f32_16x16x32_bf16 v[28:31], v[158:161], v[222:225], v[28:31]
	v_mfma_f32_16x16x32_bf16 v[24:27], v[178:181], v[222:225], v[24:27]
	v_mfma_f32_16x16x32_bf16 v[12:15], v[158:161], v[230:233], v[12:15]
	v_mfma_f32_16x16x32_bf16 v[8:11], v[178:181], v[230:233], v[8:11]
	v_mfma_f32_16x16x32_bf16 v[52:55], v[182:185], v[202:205], v[52:55]
	v_mfma_f32_16x16x32_bf16 v[48:51], v[194:197], v[202:205], v[48:51]
	v_mfma_f32_16x16x32_bf16 v[36:39], v[182:185], v[210:213], v[36:39]
	v_mfma_f32_16x16x32_bf16 v[32:35], v[194:197], v[210:213], v[32:35]
	v_mfma_f32_16x16x32_bf16 v[20:23], v[182:185], v[218:221], v[20:23]
	v_mfma_f32_16x16x32_bf16 v[16:19], v[194:197], v[218:221], v[16:19]
	v_mfma_f32_16x16x32_bf16 v[4:7], v[182:185], v[226:229], v[4:7]
	v_mfma_f32_16x16x32_bf16 v[0:3], v[194:197], v[226:229], v[0:3]
	v_mfma_f32_16x16x32_bf16 v[52:55], v[190:193], v[206:209], v[52:55]
	v_mfma_f32_16x16x32_bf16 v[48:51], v[198:201], v[206:209], v[48:51]
	v_mfma_f32_16x16x32_bf16 v[36:39], v[190:193], v[214:217], v[36:39]
	v_mfma_f32_16x16x32_bf16 v[32:35], v[198:201], v[214:217], v[32:35]
	v_mfma_f32_16x16x32_bf16 v[20:23], v[190:193], v[222:225], v[20:23]
	v_mfma_f32_16x16x32_bf16 v[16:19], v[198:201], v[222:225], v[16:19]
	v_mfma_f32_16x16x32_bf16 v[4:7], v[190:193], v[230:233], v[4:7]
	v_mfma_f32_16x16x32_bf16 v[0:3], v[198:201], v[230:233], v[0:3]
	s_barrier
	s_add_i32 s53, s53, 2
	s_add_u32 s10, s10, 0x100
	s_addc_u32 s11, s11, 0
	s_add_u32 s51, s51, 0x100
	s_addc_u32 s52, s52, 0
	s_cmp_gt_u32 s53, 5
	s_cbranch_scc0 .LBB0_947
	s_and_b64 vcc, exec, s[22:23]
	s_cbranch_vccz .LBB0_950
	s_barrier

.LBB0_1037:
	ds_read_b128 v[148:151], v160
	ds_read_b128 v[152:155], v160 offset:1024
	ds_read_b128 v[166:169], v160 offset:2048
	ds_read_b128 v[170:173], v160 offset:3072
	ds_read_b128 v[174:177], v161
	ds_read_b128 v[178:181], v161 offset:1024
	ds_read_b128 v[182:185], v161 offset:2048
	ds_read_b128 v[190:193], v161 offset:3072
	s_add_u32 s34, s10, 0xfffe0080
	s_addc_u32 s35, s11, -1
	s_cmp_eq_u32 s51, 4
	s_cselect_b32 s37, s5, s35
	s_cselect_b32 s36, s12, s34
	s_cselect_b32 s35, s23, s50
	s_cselect_b32 s34, s27, s49
	v_lshl_add_u64 v[156:157], s[10:11], 0, v[140:141]
	s_add_i32 m0, s9, 0xc000
	ds_read_b128 v[194:197], v162
	ds_read_b128 v[198:201], v162 offset:1024
	ds_read_b128 v[202:205], v162 offset:2048
	ds_read_b128 v[206:209], v162 offset:3072
	ds_read_b128 v[210:213], v162 offset:4096
	ds_read_b128 v[214:217], v162 offset:5120
	ds_read_b128 v[218:221], v162 offset:6144
	ds_read_b128 v[222:225], v162 offset:7168
	global_load_lds_dwordx4 v[156:157], off
	v_lshl_add_u64 v[156:157], s[10:11], 0, v[142:143]
	s_add_i32 m0, s9, 0xe000
	s_nop 0
	global_load_lds_dwordx4 v[156:157], off
	s_waitcnt vmcnt(8)
	s_waitcnt lgkmcnt(0)
	s_barrier
	s_waitcnt lgkmcnt(0)
	v_mfma_f32_16x16x32_bf16 v[124:127], v[148:151], v[194:197], v[124:127]
	v_mfma_f32_16x16x32_bf16 v[120:123], v[166:169], v[194:197], v[120:123]
	v_mfma_f32_16x16x32_bf16 v[108:111], v[148:151], v[202:205], v[108:111]
	v_mfma_f32_16x16x32_bf16 v[104:107], v[166:169], v[202:205], v[104:107]
	v_mfma_f32_16x16x32_bf16 v[92:95], v[148:151], v[210:213], v[92:95]
	v_mfma_f32_16x16x32_bf16 v[88:91], v[166:169], v[210:213], v[88:91]
	v_mfma_f32_16x16x32_bf16 v[76:79], v[148:151], v[218:221], v[76:79]
	v_mfma_f32_16x16x32_bf16 v[72:75], v[166:169], v[218:221], v[72:75]
	v_mfma_f32_16x16x32_bf16 v[124:127], v[152:155], v[198:201], v[124:127]
	v_mfma_f32_16x16x32_bf16 v[120:123], v[170:173], v[198:201], v[120:123]
	v_mfma_f32_16x16x32_bf16 v[108:111], v[152:155], v[206:209], v[108:111]
	v_mfma_f32_16x16x32_bf16 v[104:107], v[170:173], v[206:209], v[104:107]
	v_mfma_f32_16x16x32_bf16 v[92:95], v[152:155], v[214:217], v[92:95]
	v_mfma_f32_16x16x32_bf16 v[88:91], v[170:173], v[214:217], v[88:91]
	v_mfma_f32_16x16x32_bf16 v[76:79], v[152:155], v[222:225], v[76:79]
	v_mfma_f32_16x16x32_bf16 v[72:75], v[170:173], v[222:225], v[72:75]
	v_mfma_f32_16x16x32_bf16 v[116:119], v[174:177], v[194:197], v[116:119]
	v_mfma_f32_16x16x32_bf16 v[112:115], v[182:185], v[194:197], v[112:115]
	v_mfma_f32_16x16x32_bf16 v[100:103], v[174:177], v[202:205], v[100:103]
	v_mfma_f32_16x16x32_bf16 v[96:99], v[182:185], v[202:205], v[96:99]
	v_mfma_f32_16x16x32_bf16 v[84:87], v[174:177], v[210:213], v[84:87]
	v_mfma_f32_16x16x32_bf16 v[80:83], v[182:185], v[210:213], v[80:83]
	v_mfma_f32_16x16x32_bf16 v[68:71], v[174:177], v[218:221], v[68:71]
	v_mfma_f32_16x16x32_bf16 v[64:67], v[182:185], v[218:221], v[64:67]
	v_mfma_f32_16x16x32_bf16 v[116:119], v[178:181], v[198:201], v[116:119]
	v_mfma_f32_16x16x32_bf16 v[112:115], v[190:193], v[198:201], v[112:115]
	v_mfma_f32_16x16x32_bf16 v[100:103], v[178:181], v[206:209], v[100:103]
	v_mfma_f32_16x16x32_bf16 v[96:99], v[190:193], v[206:209], v[96:99]
	v_mfma_f32_16x16x32_bf16 v[84:87], v[178:181], v[214:217], v[84:87]
	v_mfma_f32_16x16x32_bf16 v[80:83], v[190:193], v[214:217], v[80:83]
	v_mfma_f32_16x16x32_bf16 v[68:71], v[178:181], v[222:225], v[68:71]
	v_mfma_f32_16x16x32_bf16 v[64:67], v[190:193], v[222:225], v[64:67]
	s_barrier
	s_add_i32 s52, s45, s24
	v_lshl_add_u64 v[156:157], s[34:35], 0, v[130:131]
	s_mov_b32 m0, s52
	ds_read_b128 v[194:197], v162 offset:16384
	ds_read_b128 v[198:201], v162 offset:17408
	ds_read_b128 v[202:205], v162 offset:18432
	ds_read_b128 v[206:209], v162 offset:19456
	ds_read_b128 v[210:213], v162 offset:20480
	ds_read_b128 v[214:217], v162 offset:21504
	ds_read_b128 v[218:221], v162 offset:22528
	ds_read_b128 v[222:225], v162 offset:23552
	global_load_lds_dwordx4 v[156:157], off
	s_add_i32 m0, s52, 0x2000
	s_add_u32 s52, s34, 0x20000
	v_lshl_add_u64 v[186:187], s[34:35], 0, v[134:135]
	s_addc_u32 s53, s35, 0
	s_add_i32 s54, s46, s24
	global_load_lds_dwordx4 v[186:187], off
	v_lshl_add_u64 v[226:227], s[52:53], 0, v[130:131]
	s_mov_b32 m0, s54
	v_lshl_add_u64 v[228:229], s[36:37], 0, v[132:133]
	global_load_lds_dwordx4 v[226:227], off
	v_lshl_add_u64 v[226:227], s[52:53], 0, v[134:135]
	s_add_i32 m0, s54, 0x2000
	s_nop 0
	global_load_lds_dwordx4 v[226:227], off
	v_lshl_add_u64 v[226:227], s[36:37], 0, v[128:129]
	s_mov_b32 m0, s9
	s_nop 0
	global_load_lds_dwordx4 v[226:227], off
	s_mov_b32 m0, s25
	s_nop 0
	global_load_lds_dwordx4 v[228:229], off
	s_waitcnt vmcnt(8)
	s_waitcnt lgkmcnt(0)
	s_barrier
	s_waitcnt lgkmcnt(0)
	v_mfma_f32_16x16x32_bf16 v[60:63], v[148:151], v[194:197], v[60:63]
	v_mfma_f32_16x16x32_bf16 v[56:59], v[166:169], v[194:197], v[56:59]
	v_mfma_f32_16x16x32_bf16 v[44:47], v[148:151], v[202:205], v[44:47]
	v_mfma_f32_16x16x32_bf16 v[40:43], v[166:169], v[202:205], v[40:43]
	v_mfma_f32_16x16x32_bf16 v[28:31], v[148:151], v[210:213], v[28:31]
	v_mfma_f32_16x16x32_bf16 v[24:27], v[166:169], v[210:213], v[24:27]
	v_mfma_f32_16x16x32_bf16 v[12:15], v[148:151], v[218:221], v[12:15]
	v_mfma_f32_16x16x32_bf16 v[8:11], v[166:169], v[218:221], v[8:11]
	v_mfma_f32_16x16x32_bf16 v[60:63], v[152:155], v[198:201], v[60:63]
	v_mfma_f32_16x16x32_bf16 v[56:59], v[170:173], v[198:201], v[56:59]
	v_mfma_f32_16x16x32_bf16 v[44:47], v[152:155], v[206:209], v[44:47]
	v_mfma_f32_16x16x32_bf16 v[40:43], v[170:173], v[206:209], v[40:43]
	v_mfma_f32_16x16x32_bf16 v[28:31], v[152:155], v[214:217], v[28:31]
	v_mfma_f32_16x16x32_bf16 v[24:27], v[170:173], v[214:217], v[24:27]
	v_mfma_f32_16x16x32_bf16 v[12:15], v[152:155], v[222:225], v[12:15]
	v_mfma_f32_16x16x32_bf16 v[8:11], v[170:173], v[222:225], v[8:11]
	v_mfma_f32_16x16x32_bf16 v[52:55], v[174:177], v[194:197], v[52:55]
	v_mfma_f32_16x16x32_bf16 v[48:51], v[182:185], v[194:197], v[48:51]
	v_mfma_f32_16x16x32_bf16 v[36:39], v[174:177], v[202:205], v[36:39]
	v_mfma_f32_16x16x32_bf16 v[32:35], v[182:185], v[202:205], v[32:35]
	v_mfma_f32_16x16x32_bf16 v[20:23], v[174:177], v[210:213], v[20:23]
	v_mfma_f32_16x16x32_bf16 v[16:19], v[182:185], v[210:213], v[16:19]
	v_mfma_f32_16x16x32_bf16 v[4:7], v[174:177], v[218:221], v[4:7]
	v_mfma_f32_16x16x32_bf16 v[0:3], v[182:185], v[218:221], v[0:3]
	v_mfma_f32_16x16x32_bf16 v[52:55], v[178:181], v[198:201], v[52:55]
	v_mfma_f32_16x16x32_bf16 v[48:51], v[190:193], v[198:201], v[48:51]
	v_mfma_f32_16x16x32_bf16 v[36:39], v[178:181], v[206:209], v[36:39]
	v_mfma_f32_16x16x32_bf16 v[32:35], v[190:193], v[206:209], v[32:35]
	v_mfma_f32_16x16x32_bf16 v[20:23], v[178:181], v[214:217], v[20:23]
	v_mfma_f32_16x16x32_bf16 v[16:19], v[190:193], v[214:217], v[16:19]
	v_mfma_f32_16x16x32_bf16 v[4:7], v[178:181], v[222:225], v[4:7]
	v_mfma_f32_16x16x32_bf16 v[0:3], v[190:193], v[222:225], v[0:3]
	s_barrier
	s_add_i32 s52, 0, 0x18000
	v_add_u32_e32 v165, s52, v159
	s_add_i32 s53, 0, 0x1c000
	ds_read_b128 v[148:151], v165
	ds_read_b128 v[152:155], v165 offset:1024
	ds_read_b128 v[166:169], v165 offset:2048
	ds_read_b128 v[170:173], v165 offset:3072
	v_add_u32_e32 v165, s53, v159
	ds_read_b128 v[174:177], v165
	ds_read_b128 v[178:181], v165 offset:1024
	ds_read_b128 v[182:185], v165 offset:2048
	ds_read_b128 v[190:193], v165 offset:3072
	s_add_u32 s36, s36, 0x20000
	s_addc_u32 s37, s37, 0
	s_mov_b32 m0, s38
	v_lshl_add_u64 v[230:231], s[36:37], 0, v[128:129]
	ds_read_b128 v[194:197], v162 offset:32768
	ds_read_b128 v[198:201], v162 offset:33792
	ds_read_b128 v[202:205], v162 offset:34816
	ds_read_b128 v[206:209], v162 offset:35840
	ds_read_b128 v[210:213], v162 offset:36864
	ds_read_b128 v[214:217], v162 offset:37888
	ds_read_b128 v[218:221], v162 offset:38912
	ds_read_b128 v[222:225], v162 offset:39936
	global_load_lds_dwordx4 v[230:231], off
	v_lshl_add_u64 v[230:231], s[36:37], 0, v[132:133]
	s_mov_b32 m0, s39
	s_nop 0
	global_load_lds_dwordx4 v[230:231], off
	s_waitcnt vmcnt(8)
	s_waitcnt lgkmcnt(0)
	s_barrier
	s_waitcnt lgkmcnt(0)
	v_mfma_f32_16x16x32_bf16 v[124:127], v[148:151], v[194:197], v[124:127]
	v_mfma_f32_16x16x32_bf16 v[120:123], v[166:169], v[194:197], v[120:123]
	v_mfma_f32_16x16x32_bf16 v[108:111], v[148:151], v[202:205], v[108:111]
	v_mfma_f32_16x16x32_bf16 v[104:107], v[166:169], v[202:205], v[104:107]
	v_mfma_f32_16x16x32_bf16 v[92:95], v[148:151], v[210:213], v[92:95]
	v_mfma_f32_16x16x32_bf16 v[88:91], v[166:169], v[210:213], v[88:91]
	v_mfma_f32_16x16x32_bf16 v[76:79], v[148:151], v[218:221], v[76:79]
	v_mfma_f32_16x16x32_bf16 v[72:75], v[166:169], v[218:221], v[72:75]
	v_mfma_f32_16x16x32_bf16 v[124:127], v[152:155], v[198:201], v[124:127]
	v_mfma_f32_16x16x32_bf16 v[120:123], v[170:173], v[198:201], v[120:123]
	v_mfma_f32_16x16x32_bf16 v[108:111], v[152:155], v[206:209], v[108:111]
	v_mfma_f32_16x16x32_bf16 v[104:107], v[170:173], v[206:209], v[104:107]
	v_mfma_f32_16x16x32_bf16 v[92:95], v[152:155], v[214:217], v[92:95]
	v_mfma_f32_16x16x32_bf16 v[88:91], v[170:173], v[214:217], v[88:91]
	v_mfma_f32_16x16x32_bf16 v[76:79], v[152:155], v[222:225], v[76:79]
	v_mfma_f32_16x16x32_bf16 v[72:75], v[170:173], v[222:225], v[72:75]
	v_mfma_f32_16x16x32_bf16 v[116:119], v[174:177], v[194:197], v[116:119]
	v_mfma_f32_16x16x32_bf16 v[112:115], v[182:185], v[194:197], v[112:115]
	v_mfma_f32_16x16x32_bf16 v[100:103], v[174:177], v[202:205], v[100:103]
	v_mfma_f32_16x16x32_bf16 v[96:99], v[182:185], v[202:205], v[96:99]
	v_mfma_f32_16x16x32_bf16 v[84:87], v[174:177], v[210:213], v[84:87]
	v_mfma_f32_16x16x32_bf16 v[80:83], v[182:185], v[210:213], v[80:83]
	v_mfma_f32_16x16x32_bf16 v[68:71], v[174:177], v[218:221], v[68:71]
	v_mfma_f32_16x16x32_bf16 v[64:67], v[182:185], v[218:221], v[64:67]
	v_mfma_f32_16x16x32_bf16 v[116:119], v[178:181], v[198:201], v[116:119]
	v_mfma_f32_16x16x32_bf16 v[112:115], v[190:193], v[198:201], v[112:115]
	v_mfma_f32_16x16x32_bf16 v[100:103], v[178:181], v[206:209], v[100:103]
	v_mfma_f32_16x16x32_bf16 v[96:99], v[190:193], v[206:209], v[96:99]
	v_mfma_f32_16x16x32_bf16 v[84:87], v[178:181], v[214:217], v[84:87]
	v_mfma_f32_16x16x32_bf16 v[80:83], v[190:193], v[214:217], v[80:83]
	v_mfma_f32_16x16x32_bf16 v[68:71], v[178:181], v[222:225], v[68:71]
	v_mfma_f32_16x16x32_bf16 v[64:67], v[190:193], v[222:225], v[64:67]
	s_barrier
	s_add_i32 s36, s52, s24
	v_lshl_add_u64 v[156:157], v[156:157], 0, s[16:17]
	s_mov_b32 m0, s36
	ds_read_b128 v[194:197], v162 offset:49152
	ds_read_b128 v[198:201], v162 offset:50176
	ds_read_b128 v[202:205], v162 offset:51200
	ds_read_b128 v[206:209], v162 offset:52224
	ds_read_b128 v[210:213], v162 offset:53248
	ds_read_b128 v[214:217], v162 offset:54272
	ds_read_b128 v[218:221], v162 offset:55296
	ds_read_b128 v[222:225], v162 offset:56320
	global_load_lds_dwordx4 v[156:157], off
	s_add_i32 m0, s36, 0x2000
	s_add_u32 s34, s34, 0x20080
	v_lshl_add_u64 v[156:157], v[186:187], 0, s[16:17]
	s_addc_u32 s35, s35, 0
	s_add_i32 s36, s53, s24
	global_load_lds_dwordx4 v[156:157], off
	v_lshl_add_u64 v[156:157], s[34:35], 0, v[130:131]
	s_mov_b32 m0, s36
	s_nop 0
	global_load_lds_dwordx4 v[156:157], off
	v_lshl_add_u64 v[156:157], s[34:35], 0, v[134:135]
	s_add_i32 m0, s36, 0x2000
	s_nop 0
	global_load_lds_dwordx4 v[156:157], off
	v_lshl_add_u64 v[156:157], v[226:227], 0, s[16:17]
	s_mov_b32 m0, s41
	s_nop 0
	global_load_lds_dwordx4 v[156:157], off
	v_lshl_add_u64 v[156:157], v[228:229], 0, s[16:17]
	s_mov_b32 m0, s42
	s_nop 0
	global_load_lds_dwordx4 v[156:157], off
	s_waitcnt vmcnt(8)
	s_waitcnt lgkmcnt(0)
	s_barrier
	s_waitcnt lgkmcnt(0)
	v_mfma_f32_16x16x32_bf16 v[60:63], v[148:151], v[194:197], v[60:63]
	v_mfma_f32_16x16x32_bf16 v[56:59], v[166:169], v[194:197], v[56:59]
	v_mfma_f32_16x16x32_bf16 v[44:47], v[148:151], v[202:205], v[44:47]
	v_mfma_f32_16x16x32_bf16 v[40:43], v[166:169], v[202:205], v[40:43]
	v_mfma_f32_16x16x32_bf16 v[28:31], v[148:151], v[210:213], v[28:31]
	v_mfma_f32_16x16x32_bf16 v[24:27], v[166:169], v[210:213], v[24:27]
	v_mfma_f32_16x16x32_bf16 v[12:15], v[148:151], v[218:221], v[12:15]
	v_mfma_f32_16x16x32_bf16 v[8:11], v[166:169], v[218:221], v[8:11]
	v_mfma_f32_16x16x32_bf16 v[60:63], v[152:155], v[198:201], v[60:63]
	v_mfma_f32_16x16x32_bf16 v[56:59], v[170:173], v[198:201], v[56:59]
	v_mfma_f32_16x16x32_bf16 v[44:47], v[152:155], v[206:209], v[44:47]
	v_mfma_f32_16x16x32_bf16 v[40:43], v[170:173], v[206:209], v[40:43]
	v_mfma_f32_16x16x32_bf16 v[28:31], v[152:155], v[214:217], v[28:31]
	v_mfma_f32_16x16x32_bf16 v[24:27], v[170:173], v[214:217], v[24:27]
	v_mfma_f32_16x16x32_bf16 v[12:15], v[152:155], v[222:225], v[12:15]
	v_mfma_f32_16x16x32_bf16 v[8:11], v[170:173], v[222:225], v[8:11]
	v_mfma_f32_16x16x32_bf16 v[52:55], v[174:177], v[194:197], v[52:55]
	v_mfma_f32_16x16x32_bf16 v[48:51], v[182:185], v[194:197], v[48:51]
	v_mfma_f32_16x16x32_bf16 v[36:39], v[174:177], v[202:205], v[36:39]
	v_mfma_f32_16x16x32_bf16 v[32:35], v[182:185], v[202:205], v[32:35]
	v_mfma_f32_16x16x32_bf16 v[20:23], v[174:177], v[210:213], v[20:23]
	v_mfma_f32_16x16x32_bf16 v[16:19], v[182:185], v[210:213], v[16:19]
	v_mfma_f32_16x16x32_bf16 v[4:7], v[174:177], v[218:221], v[4:7]
	v_mfma_f32_16x16x32_bf16 v[0:3], v[182:185], v[218:221], v[0:3]
	v_mfma_f32_16x16x32_bf16 v[52:55], v[178:181], v[198:201], v[52:55]
	v_mfma_f32_16x16x32_bf16 v[48:51], v[190:193], v[198:201], v[48:51]
	v_mfma_f32_16x16x32_bf16 v[36:39], v[178:181], v[206:209], v[36:39]
	v_mfma_f32_16x16x32_bf16 v[32:35], v[190:193], v[206:209], v[32:35]
	v_mfma_f32_16x16x32_bf16 v[20:23], v[178:181], v[214:217], v[20:23]
	v_mfma_f32_16x16x32_bf16 v[16:19], v[190:193], v[214:217], v[16:19]
	v_mfma_f32_16x16x32_bf16 v[4:7], v[178:181], v[222:225], v[4:7]
	v_mfma_f32_16x16x32_bf16 v[0:3], v[190:193], v[222:225], v[0:3]
	s_barrier
	s_add_i32 s51, s51, 2
	s_add_u32 s10, s10, 0x100
	s_addc_u32 s11, s11, 0
	s_add_u32 s49, s49, 0x100
	s_addc_u32 s50, s50, 0
	s_cmp_gt_u32 s51, 5
	s_cbranch_scc0 .LBB0_1037
	s_and_b64 vcc, exec, s[18:19]
	s_cbranch_vccz .LBB0_1040
	s_barrier

.LBB0_1452:
	ds_read_b128 v[128:131], v177
	ds_read_b128 v[132:135], v177 offset:1024
	ds_read_b128 v[136:139], v177 offset:2048
	ds_read_b128 v[140:143], v177 offset:3072
	ds_read_b128 v[160:163], v178
	ds_read_b128 v[164:167], v178 offset:1024
	ds_read_b128 v[168:171], v178 offset:2048
	ds_read_b128 v[182:185], v178 offset:3072
	s_add_u32 s28, s26, 0xfff80080
	s_addc_u32 s29, s27, -1
	s_cmp_eq_u32 s50, 28
	s_cselect_b32 s31, s15, s29
	s_cselect_b32 s30, s23, s28
	s_cselect_b32 s29, s17, s49
	s_cselect_b32 s28, s25, s48
	v_lshl_add_u64 v[172:173], s[26:27], 0, v[152:153]
	s_add_i32 m0, s34, 0xc000
	ds_read_b128 v[190:193], v179
	ds_read_b128 v[194:197], v179 offset:1024
	ds_read_b128 v[198:201], v179 offset:2048
	ds_read_b128 v[202:205], v179 offset:3072
	ds_read_b128 v[206:209], v179 offset:4096
	ds_read_b128 v[210:213], v179 offset:5120
	ds_read_b128 v[214:217], v179 offset:6144
	ds_read_b128 v[218:221], v179 offset:7168
	global_load_lds_dwordx4 v[172:173], off
	v_lshl_add_u64 v[172:173], s[26:27], 0, v[154:155]
	s_add_i32 m0, s34, 0xe000
	s_nop 0
	global_load_lds_dwordx4 v[172:173], off
	s_waitcnt vmcnt(8)
	s_waitcnt lgkmcnt(0)
	s_barrier
	s_waitcnt lgkmcnt(0)
	v_mfma_f32_16x16x32_bf16 v[124:127], v[128:131], v[190:193], v[124:127]
	v_mfma_f32_16x16x32_bf16 v[120:123], v[136:139], v[190:193], v[120:123]
	v_mfma_f32_16x16x32_bf16 v[108:111], v[128:131], v[198:201], v[108:111]
	v_mfma_f32_16x16x32_bf16 v[104:107], v[136:139], v[198:201], v[104:107]
	v_mfma_f32_16x16x32_bf16 v[92:95], v[128:131], v[206:209], v[92:95]
	v_mfma_f32_16x16x32_bf16 v[88:91], v[136:139], v[206:209], v[88:91]
	v_mfma_f32_16x16x32_bf16 v[76:79], v[128:131], v[214:217], v[76:79]
	v_mfma_f32_16x16x32_bf16 v[72:75], v[136:139], v[214:217], v[72:75]
	v_mfma_f32_16x16x32_bf16 v[124:127], v[132:135], v[194:197], v[124:127]
	v_mfma_f32_16x16x32_bf16 v[120:123], v[140:143], v[194:197], v[120:123]
	v_mfma_f32_16x16x32_bf16 v[108:111], v[132:135], v[202:205], v[108:111]
	v_mfma_f32_16x16x32_bf16 v[104:107], v[140:143], v[202:205], v[104:107]
	v_mfma_f32_16x16x32_bf16 v[92:95], v[132:135], v[210:213], v[92:95]
	v_mfma_f32_16x16x32_bf16 v[88:91], v[140:143], v[210:213], v[88:91]
	v_mfma_f32_16x16x32_bf16 v[76:79], v[132:135], v[218:221], v[76:79]
	v_mfma_f32_16x16x32_bf16 v[72:75], v[140:143], v[218:221], v[72:75]
	v_mfma_f32_16x16x32_bf16 v[116:119], v[160:163], v[190:193], v[116:119]
	v_mfma_f32_16x16x32_bf16 v[112:115], v[168:171], v[190:193], v[112:115]
	v_mfma_f32_16x16x32_bf16 v[100:103], v[160:163], v[198:201], v[100:103]
	v_mfma_f32_16x16x32_bf16 v[96:99], v[168:171], v[198:201], v[96:99]
	v_mfma_f32_16x16x32_bf16 v[84:87], v[160:163], v[206:209], v[84:87]
	v_mfma_f32_16x16x32_bf16 v[80:83], v[168:171], v[206:209], v[80:83]
	v_mfma_f32_16x16x32_bf16 v[68:71], v[160:163], v[214:217], v[68:71]
	v_mfma_f32_16x16x32_bf16 v[64:67], v[168:171], v[214:217], v[64:67]
	v_mfma_f32_16x16x32_bf16 v[116:119], v[164:167], v[194:197], v[116:119]
	v_mfma_f32_16x16x32_bf16 v[112:115], v[182:185], v[194:197], v[112:115]
	v_mfma_f32_16x16x32_bf16 v[100:103], v[164:167], v[202:205], v[100:103]
	v_mfma_f32_16x16x32_bf16 v[96:99], v[182:185], v[202:205], v[96:99]
	v_mfma_f32_16x16x32_bf16 v[84:87], v[164:167], v[210:213], v[84:87]
	v_mfma_f32_16x16x32_bf16 v[80:83], v[182:185], v[210:213], v[80:83]
	v_mfma_f32_16x16x32_bf16 v[68:71], v[164:167], v[218:221], v[68:71]
	v_mfma_f32_16x16x32_bf16 v[64:67], v[182:185], v[218:221], v[64:67]
	s_barrier
	s_add_i32 s51, s45, s33
	v_lshl_add_u64 v[172:173], s[28:29], 0, v[146:147]
	s_mov_b32 m0, s51
	ds_read_b128 v[190:193], v179 offset:16384
	ds_read_b128 v[194:197], v179 offset:17408
	ds_read_b128 v[198:201], v179 offset:18432
	ds_read_b128 v[202:205], v179 offset:19456
	ds_read_b128 v[206:209], v179 offset:20480
	ds_read_b128 v[210:213], v179 offset:21504
	ds_read_b128 v[214:217], v179 offset:22528
	ds_read_b128 v[218:221], v179 offset:23552
	global_load_lds_dwordx4 v[172:173], off
	s_add_i32 m0, s51, 0x2000
	s_add_u32 s52, s28, 0x80000
	v_lshl_add_u64 v[186:187], s[28:29], 0, v[150:151]
	s_addc_u32 s53, s29, 0
	s_add_i32 s51, s46, s33
	global_load_lds_dwordx4 v[186:187], off
	v_lshl_add_u64 v[222:223], s[52:53], 0, v[146:147]
	s_mov_b32 m0, s51
	v_lshl_add_u64 v[224:225], s[30:31], 0, v[148:149]
	global_load_lds_dwordx4 v[222:223], off
	v_lshl_add_u64 v[222:223], s[52:53], 0, v[150:151]
	s_add_i32 m0, s51, 0x2000
	s_nop 0
	global_load_lds_dwordx4 v[222:223], off
	v_lshl_add_u64 v[222:223], s[30:31], 0, v[144:145]
	s_mov_b32 m0, s34
	s_nop 0
	global_load_lds_dwordx4 v[222:223], off
	s_mov_b32 m0, s35
	s_nop 0
	global_load_lds_dwordx4 v[224:225], off
	s_waitcnt vmcnt(8)
	s_waitcnt lgkmcnt(0)
	s_barrier
	s_waitcnt lgkmcnt(0)
	v_mfma_f32_16x16x32_bf16 v[60:63], v[128:131], v[190:193], v[60:63]
	v_mfma_f32_16x16x32_bf16 v[56:59], v[136:139], v[190:193], v[56:59]
	v_mfma_f32_16x16x32_bf16 v[44:47], v[128:131], v[198:201], v[44:47]
	v_mfma_f32_16x16x32_bf16 v[40:43], v[136:139], v[198:201], v[40:43]
	v_mfma_f32_16x16x32_bf16 v[28:31], v[128:131], v[206:209], v[28:31]
	v_mfma_f32_16x16x32_bf16 v[24:27], v[136:139], v[206:209], v[24:27]
	v_mfma_f32_16x16x32_bf16 v[12:15], v[128:131], v[214:217], v[12:15]
	v_mfma_f32_16x16x32_bf16 v[8:11], v[136:139], v[214:217], v[8:11]
	v_mfma_f32_16x16x32_bf16 v[60:63], v[132:135], v[194:197], v[60:63]
	v_mfma_f32_16x16x32_bf16 v[56:59], v[140:143], v[194:197], v[56:59]
	v_mfma_f32_16x16x32_bf16 v[44:47], v[132:135], v[202:205], v[44:47]
	v_mfma_f32_16x16x32_bf16 v[40:43], v[140:143], v[202:205], v[40:43]
	v_mfma_f32_16x16x32_bf16 v[28:31], v[132:135], v[210:213], v[28:31]
	v_mfma_f32_16x16x32_bf16 v[24:27], v[140:143], v[210:213], v[24:27]
	v_mfma_f32_16x16x32_bf16 v[12:15], v[132:135], v[218:221], v[12:15]
	v_mfma_f32_16x16x32_bf16 v[8:11], v[140:143], v[218:221], v[8:11]
	v_mfma_f32_16x16x32_bf16 v[52:55], v[160:163], v[190:193], v[52:55]
	v_mfma_f32_16x16x32_bf16 v[48:51], v[168:171], v[190:193], v[48:51]
	v_mfma_f32_16x16x32_bf16 v[36:39], v[160:163], v[198:201], v[36:39]
	v_mfma_f32_16x16x32_bf16 v[32:35], v[168:171], v[198:201], v[32:35]
	v_mfma_f32_16x16x32_bf16 v[20:23], v[160:163], v[206:209], v[20:23]
	v_mfma_f32_16x16x32_bf16 v[16:19], v[168:171], v[206:209], v[16:19]
	v_mfma_f32_16x16x32_bf16 v[4:7], v[160:163], v[214:217], v[4:7]
	v_mfma_f32_16x16x32_bf16 v[0:3], v[168:171], v[214:217], v[0:3]
	v_mfma_f32_16x16x32_bf16 v[52:55], v[164:167], v[194:197], v[52:55]
	v_mfma_f32_16x16x32_bf16 v[48:51], v[182:185], v[194:197], v[48:51]
	v_mfma_f32_16x16x32_bf16 v[36:39], v[164:167], v[202:205], v[36:39]
	v_mfma_f32_16x16x32_bf16 v[32:35], v[182:185], v[202:205], v[32:35]
	v_mfma_f32_16x16x32_bf16 v[20:23], v[164:167], v[210:213], v[20:23]
	v_mfma_f32_16x16x32_bf16 v[16:19], v[182:185], v[210:213], v[16:19]
	v_mfma_f32_16x16x32_bf16 v[4:7], v[164:167], v[218:221], v[4:7]
	v_mfma_f32_16x16x32_bf16 v[0:3], v[182:185], v[218:221], v[0:3]
	s_barrier
	s_add_i32 s51, 0, 0x18000
	s_add_i32 s52, 0, 0x1c000
	v_add_u32_e32 v140, s51, v175
	v_add_u32_e32 v181, s52, v175
	ds_read_b128 v[128:131], v140
	ds_read_b128 v[132:135], v140 offset:1024
	ds_read_b128 v[136:139], v140 offset:2048
	ds_read_b128 v[140:143], v140 offset:3072
	ds_read_b128 v[160:163], v181
	ds_read_b128 v[164:167], v181 offset:1024
	ds_read_b128 v[168:171], v181 offset:2048
	ds_read_b128 v[182:185], v181 offset:3072
	s_add_u32 s30, s30, 0x80000
	s_addc_u32 s31, s31, 0
	s_mov_b32 m0, s36
	v_lshl_add_u64 v[226:227], s[30:31], 0, v[144:145]
	ds_read_b128 v[190:193], v179 offset:32768
	ds_read_b128 v[194:197], v179 offset:33792
	ds_read_b128 v[198:201], v179 offset:34816
	ds_read_b128 v[202:205], v179 offset:35840
	ds_read_b128 v[206:209], v179 offset:36864
	ds_read_b128 v[210:213], v179 offset:37888
	ds_read_b128 v[214:217], v179 offset:38912
	ds_read_b128 v[218:221], v179 offset:39936
	global_load_lds_dwordx4 v[226:227], off
	v_lshl_add_u64 v[226:227], s[30:31], 0, v[148:149]
	s_mov_b32 m0, s37
	s_nop 0
	global_load_lds_dwordx4 v[226:227], off
	s_waitcnt vmcnt(8)
	s_waitcnt lgkmcnt(0)
	s_barrier
	s_waitcnt lgkmcnt(0)
	v_mfma_f32_16x16x32_bf16 v[124:127], v[128:131], v[190:193], v[124:127]
	v_mfma_f32_16x16x32_bf16 v[120:123], v[136:139], v[190:193], v[120:123]
	v_mfma_f32_16x16x32_bf16 v[108:111], v[128:131], v[198:201], v[108:111]
	v_mfma_f32_16x16x32_bf16 v[104:107], v[136:139], v[198:201], v[104:107]
	v_mfma_f32_16x16x32_bf16 v[92:95], v[128:131], v[206:209], v[92:95]
	v_mfma_f32_16x16x32_bf16 v[88:91], v[136:139], v[206:209], v[88:91]
	v_mfma_f32_16x16x32_bf16 v[76:79], v[128:131], v[214:217], v[76:79]
	v_mfma_f32_16x16x32_bf16 v[72:75], v[136:139], v[214:217], v[72:75]
	v_mfma_f32_16x16x32_bf16 v[124:127], v[132:135], v[194:197], v[124:127]
	v_mfma_f32_16x16x32_bf16 v[120:123], v[140:143], v[194:197], v[120:123]
	v_mfma_f32_16x16x32_bf16 v[108:111], v[132:135], v[202:205], v[108:111]
	v_mfma_f32_16x16x32_bf16 v[104:107], v[140:143], v[202:205], v[104:107]
	v_mfma_f32_16x16x32_bf16 v[92:95], v[132:135], v[210:213], v[92:95]
	v_mfma_f32_16x16x32_bf16 v[88:91], v[140:143], v[210:213], v[88:91]
	v_mfma_f32_16x16x32_bf16 v[76:79], v[132:135], v[218:221], v[76:79]
	v_mfma_f32_16x16x32_bf16 v[72:75], v[140:143], v[218:221], v[72:75]
	v_mfma_f32_16x16x32_bf16 v[116:119], v[160:163], v[190:193], v[116:119]
	v_mfma_f32_16x16x32_bf16 v[112:115], v[168:171], v[190:193], v[112:115]
	v_mfma_f32_16x16x32_bf16 v[100:103], v[160:163], v[198:201], v[100:103]
	v_mfma_f32_16x16x32_bf16 v[96:99], v[168:171], v[198:201], v[96:99]
	v_mfma_f32_16x16x32_bf16 v[84:87], v[160:163], v[206:209], v[84:87]
	v_mfma_f32_16x16x32_bf16 v[80:83], v[168:171], v[206:209], v[80:83]
	v_mfma_f32_16x16x32_bf16 v[68:71], v[160:163], v[214:217], v[68:71]
	v_mfma_f32_16x16x32_bf16 v[64:67], v[168:171], v[214:217], v[64:67]
	v_mfma_f32_16x16x32_bf16 v[116:119], v[164:167], v[194:197], v[116:119]
	v_mfma_f32_16x16x32_bf16 v[112:115], v[182:185], v[194:197], v[112:115]
	v_mfma_f32_16x16x32_bf16 v[100:103], v[164:167], v[202:205], v[100:103]
	v_mfma_f32_16x16x32_bf16 v[96:99], v[182:185], v[202:205], v[96:99]
	v_mfma_f32_16x16x32_bf16 v[84:87], v[164:167], v[210:213], v[84:87]
	v_mfma_f32_16x16x32_bf16 v[80:83], v[182:185], v[210:213], v[80:83]
	v_mfma_f32_16x16x32_bf16 v[68:71], v[164:167], v[218:221], v[68:71]
	v_mfma_f32_16x16x32_bf16 v[64:67], v[182:185], v[218:221], v[64:67]
	s_barrier
	s_add_i32 s30, s51, s33
	v_lshl_add_u64 v[172:173], v[172:173], 0, s[8:9]
	s_mov_b32 m0, s30
	ds_read_b128 v[190:193], v179 offset:49152
	ds_read_b128 v[194:197], v179 offset:50176
	ds_read_b128 v[198:201], v179 offset:51200
	ds_read_b128 v[202:205], v179 offset:52224
	ds_read_b128 v[206:209], v179 offset:53248
	ds_read_b128 v[210:213], v179 offset:54272
	ds_read_b128 v[214:217], v179 offset:55296
	ds_read_b128 v[218:221], v179 offset:56320
	global_load_lds_dwordx4 v[172:173], off
	s_add_i32 m0, s30, 0x2000
	s_add_u32 s28, s28, 0x80080
	v_lshl_add_u64 v[172:173], v[186:187], 0, s[8:9]
	s_addc_u32 s29, s29, 0
	s_add_i32 s30, s52, s33
	global_load_lds_dwordx4 v[172:173], off
	v_lshl_add_u64 v[172:173], s[28:29], 0, v[146:147]
	s_mov_b32 m0, s30
	s_nop 0
	global_load_lds_dwordx4 v[172:173], off
	v_lshl_add_u64 v[172:173], s[28:29], 0, v[150:151]
	s_add_i32 m0, s30, 0x2000
	s_nop 0
	global_load_lds_dwordx4 v[172:173], off
	v_lshl_add_u64 v[172:173], v[222:223], 0, s[8:9]
	s_mov_b32 m0, s41
	s_nop 0
	global_load_lds_dwordx4 v[172:173], off
	v_lshl_add_u64 v[172:173], v[224:225], 0, s[8:9]
	s_mov_b32 m0, s42
	s_nop 0
	global_load_lds_dwordx4 v[172:173], off
	s_waitcnt vmcnt(8)
	s_waitcnt lgkmcnt(0)
	s_barrier
	s_waitcnt lgkmcnt(0)
	v_mfma_f32_16x16x32_bf16 v[60:63], v[128:131], v[190:193], v[60:63]
	v_mfma_f32_16x16x32_bf16 v[56:59], v[136:139], v[190:193], v[56:59]
	v_mfma_f32_16x16x32_bf16 v[44:47], v[128:131], v[198:201], v[44:47]
	v_mfma_f32_16x16x32_bf16 v[40:43], v[136:139], v[198:201], v[40:43]
	v_mfma_f32_16x16x32_bf16 v[28:31], v[128:131], v[206:209], v[28:31]
	v_mfma_f32_16x16x32_bf16 v[24:27], v[136:139], v[206:209], v[24:27]
	v_mfma_f32_16x16x32_bf16 v[12:15], v[128:131], v[214:217], v[12:15]
	v_mfma_f32_16x16x32_bf16 v[8:11], v[136:139], v[214:217], v[8:11]
	v_mfma_f32_16x16x32_bf16 v[60:63], v[132:135], v[194:197], v[60:63]
	v_mfma_f32_16x16x32_bf16 v[56:59], v[140:143], v[194:197], v[56:59]
	v_mfma_f32_16x16x32_bf16 v[44:47], v[132:135], v[202:205], v[44:47]
	v_mfma_f32_16x16x32_bf16 v[40:43], v[140:143], v[202:205], v[40:43]
	v_mfma_f32_16x16x32_bf16 v[28:31], v[132:135], v[210:213], v[28:31]
	v_mfma_f32_16x16x32_bf16 v[24:27], v[140:143], v[210:213], v[24:27]
	v_mfma_f32_16x16x32_bf16 v[12:15], v[132:135], v[218:221], v[12:15]
	v_mfma_f32_16x16x32_bf16 v[8:11], v[140:143], v[218:221], v[8:11]
	v_mfma_f32_16x16x32_bf16 v[52:55], v[160:163], v[190:193], v[52:55]
	v_mfma_f32_16x16x32_bf16 v[48:51], v[168:171], v[190:193], v[48:51]
	v_mfma_f32_16x16x32_bf16 v[36:39], v[160:163], v[198:201], v[36:39]
	v_mfma_f32_16x16x32_bf16 v[32:35], v[168:171], v[198:201], v[32:35]
	v_mfma_f32_16x16x32_bf16 v[20:23], v[160:163], v[206:209], v[20:23]
	v_mfma_f32_16x16x32_bf16 v[16:19], v[168:171], v[206:209], v[16:19]
	v_mfma_f32_16x16x32_bf16 v[4:7], v[160:163], v[214:217], v[4:7]
	v_mfma_f32_16x16x32_bf16 v[0:3], v[168:171], v[214:217], v[0:3]
	v_mfma_f32_16x16x32_bf16 v[52:55], v[164:167], v[194:197], v[52:55]
	v_mfma_f32_16x16x32_bf16 v[48:51], v[182:185], v[194:197], v[48:51]
	v_mfma_f32_16x16x32_bf16 v[36:39], v[164:167], v[202:205], v[36:39]
	v_mfma_f32_16x16x32_bf16 v[32:35], v[182:185], v[202:205], v[32:35]
	v_mfma_f32_16x16x32_bf16 v[20:23], v[164:167], v[210:213], v[20:23]
	v_mfma_f32_16x16x32_bf16 v[16:19], v[182:185], v[210:213], v[16:19]
	v_mfma_f32_16x16x32_bf16 v[4:7], v[164:167], v[218:221], v[4:7]
	v_mfma_f32_16x16x32_bf16 v[0:3], v[182:185], v[218:221], v[0:3]
	s_barrier
	s_add_i32 s50, s50, 2
	s_add_u32 s26, s26, 0x100
	s_addc_u32 s27, s27, 0
	s_add_u32 s48, s48, 0x100
	s_addc_u32 s49, s49, 0
	s_cmp_gt_u32 s50, 29
	s_cbranch_scc0 .LBB0_1452
	s_and_b64 vcc, exec, s[10:11]
	s_cbranch_vccz .LBB0_1455
	s_barrier

.LBB0_1539:
	ds_read_b128 v[156:159], v151
	ds_read_b128 v[160:163], v151 offset:1024
	ds_read_b128 v[164:167], v151 offset:2048
	ds_read_b128 v[168:171], v151 offset:3072
	ds_read_b128 v[172:175], v152
	ds_read_b128 v[176:179], v152 offset:1024
	ds_read_b128 v[180:183], v152 offset:2048
	ds_read_b128 v[184:187], v152 offset:3072
	s_add_u32 s22, s20, 0xfff80080
	s_addc_u32 s23, s21, -1
	s_cmp_eq_u32 s48, 28
	s_cselect_b32 s25, s11, s23
	s_cselect_b32 s24, s44, s22
	s_cselect_b32 s23, s13, s47
	s_cselect_b32 s22, s45, s46
	v_lshl_add_u64 v[146:147], s[20:21], 0, v[138:139]
	s_add_i32 m0, s19, 0xc000
	ds_read_b128 v[190:193], v153
	ds_read_b128 v[194:197], v153 offset:1024
	ds_read_b128 v[198:201], v153 offset:2048
	ds_read_b128 v[202:205], v153 offset:3072
	ds_read_b128 v[206:209], v153 offset:4096
	ds_read_b128 v[210:213], v153 offset:5120
	ds_read_b128 v[214:217], v153 offset:6144
	ds_read_b128 v[218:221], v153 offset:7168
	global_load_lds_dwordx4 v[146:147], off
	v_lshl_add_u64 v[146:147], s[20:21], 0, v[140:141]
	s_add_i32 m0, s19, 0xe000
	s_nop 0
	global_load_lds_dwordx4 v[146:147], off
	s_waitcnt vmcnt(8)
	s_waitcnt lgkmcnt(0)
	s_barrier
	s_waitcnt lgkmcnt(0)
	v_mfma_f32_16x16x32_bf16 v[116:119], v[156:159], v[190:193], v[116:119]
	v_mfma_f32_16x16x32_bf16 v[112:115], v[164:167], v[190:193], v[112:115]
	v_mfma_f32_16x16x32_bf16 v[100:103], v[156:159], v[198:201], v[100:103]
	v_mfma_f32_16x16x32_bf16 v[96:99], v[164:167], v[198:201], v[96:99]
	v_mfma_f32_16x16x32_bf16 v[84:87], v[156:159], v[206:209], v[84:87]
	v_mfma_f32_16x16x32_bf16 v[80:83], v[164:167], v[206:209], v[80:83]
	v_mfma_f32_16x16x32_bf16 v[68:71], v[156:159], v[214:217], v[68:71]
	v_mfma_f32_16x16x32_bf16 v[64:67], v[164:167], v[214:217], v[64:67]
	v_mfma_f32_16x16x32_bf16 v[116:119], v[160:163], v[194:197], v[116:119]
	v_mfma_f32_16x16x32_bf16 v[112:115], v[168:171], v[194:197], v[112:115]
	v_mfma_f32_16x16x32_bf16 v[100:103], v[160:163], v[202:205], v[100:103]
	v_mfma_f32_16x16x32_bf16 v[96:99], v[168:171], v[202:205], v[96:99]
	v_mfma_f32_16x16x32_bf16 v[84:87], v[160:163], v[210:213], v[84:87]
	v_mfma_f32_16x16x32_bf16 v[80:83], v[168:171], v[210:213], v[80:83]
	v_mfma_f32_16x16x32_bf16 v[68:71], v[160:163], v[218:221], v[68:71]
	v_mfma_f32_16x16x32_bf16 v[64:67], v[168:171], v[218:221], v[64:67]
	v_mfma_f32_16x16x32_bf16 v[124:127], v[172:175], v[190:193], v[124:127]
	v_mfma_f32_16x16x32_bf16 v[120:123], v[180:183], v[190:193], v[120:123]
	v_mfma_f32_16x16x32_bf16 v[108:111], v[172:175], v[198:201], v[108:111]
	v_mfma_f32_16x16x32_bf16 v[104:107], v[180:183], v[198:201], v[104:107]
	v_mfma_f32_16x16x32_bf16 v[92:95], v[172:175], v[206:209], v[92:95]
	v_mfma_f32_16x16x32_bf16 v[88:91], v[180:183], v[206:209], v[88:91]
	v_mfma_f32_16x16x32_bf16 v[76:79], v[172:175], v[214:217], v[76:79]
	v_mfma_f32_16x16x32_bf16 v[72:75], v[180:183], v[214:217], v[72:75]
	v_mfma_f32_16x16x32_bf16 v[124:127], v[176:179], v[194:197], v[124:127]
	v_mfma_f32_16x16x32_bf16 v[120:123], v[184:187], v[194:197], v[120:123]
	v_mfma_f32_16x16x32_bf16 v[108:111], v[176:179], v[202:205], v[108:111]
	v_mfma_f32_16x16x32_bf16 v[104:107], v[184:187], v[202:205], v[104:107]
	v_mfma_f32_16x16x32_bf16 v[92:95], v[176:179], v[210:213], v[92:95]
	v_mfma_f32_16x16x32_bf16 v[88:91], v[184:187], v[210:213], v[88:91]
	v_mfma_f32_16x16x32_bf16 v[76:79], v[176:179], v[218:221], v[76:79]
	v_mfma_f32_16x16x32_bf16 v[72:75], v[184:187], v[218:221], v[72:75]
	s_barrier
	s_add_i32 s49, s40, s28
	v_lshl_add_u64 v[146:147], s[22:23], 0, v[132:133]
	s_mov_b32 m0, s49
	ds_read_b128 v[190:193], v153 offset:16384
	ds_read_b128 v[194:197], v153 offset:17408
	ds_read_b128 v[198:201], v153 offset:18432
	ds_read_b128 v[202:205], v153 offset:19456
	ds_read_b128 v[206:209], v153 offset:20480
	ds_read_b128 v[210:213], v153 offset:21504
	ds_read_b128 v[214:217], v153 offset:22528
	ds_read_b128 v[218:221], v153 offset:23552
	global_load_lds_dwordx4 v[146:147], off
	s_add_i32 m0, s49, 0x2000
	s_add_u32 s50, s22, 0x80000
	v_lshl_add_u64 v[222:223], s[22:23], 0, v[128:129]
	s_addc_u32 s51, s23, 0
	s_add_i32 s49, s41, s28
	global_load_lds_dwordx4 v[222:223], off
	v_lshl_add_u64 v[224:225], s[50:51], 0, v[132:133]
	s_mov_b32 m0, s49
	v_lshl_add_u64 v[226:227], s[24:25], 0, v[130:131]
	global_load_lds_dwordx4 v[224:225], off
	v_lshl_add_u64 v[224:225], s[50:51], 0, v[128:129]
	s_add_i32 m0, s49, 0x2000
	s_nop 0
	global_load_lds_dwordx4 v[224:225], off
	v_lshl_add_u64 v[224:225], s[24:25], 0, v[134:135]
	s_mov_b32 m0, s19
	s_nop 0
	global_load_lds_dwordx4 v[224:225], off
	s_mov_b32 m0, s30
	s_nop 0
	global_load_lds_dwordx4 v[226:227], off
	s_waitcnt vmcnt(8)
	s_waitcnt lgkmcnt(0)
	s_barrier
	s_waitcnt lgkmcnt(0)
	v_mfma_f32_16x16x32_bf16 v[52:55], v[156:159], v[190:193], v[52:55]
	v_mfma_f32_16x16x32_bf16 v[48:51], v[164:167], v[190:193], v[48:51]
	v_mfma_f32_16x16x32_bf16 v[36:39], v[156:159], v[198:201], v[36:39]
	v_mfma_f32_16x16x32_bf16 v[32:35], v[164:167], v[198:201], v[32:35]
	v_mfma_f32_16x16x32_bf16 v[20:23], v[156:159], v[206:209], v[20:23]
	v_mfma_f32_16x16x32_bf16 v[16:19], v[164:167], v[206:209], v[16:19]
	v_mfma_f32_16x16x32_bf16 v[8:11], v[156:159], v[214:217], v[8:11]
	v_mfma_f32_16x16x32_bf16 v[0:3], v[164:167], v[214:217], v[0:3]
	v_mfma_f32_16x16x32_bf16 v[52:55], v[160:163], v[194:197], v[52:55]
	v_mfma_f32_16x16x32_bf16 v[48:51], v[168:171], v[194:197], v[48:51]
	v_mfma_f32_16x16x32_bf16 v[36:39], v[160:163], v[202:205], v[36:39]
	v_mfma_f32_16x16x32_bf16 v[32:35], v[168:171], v[202:205], v[32:35]
	v_mfma_f32_16x16x32_bf16 v[20:23], v[160:163], v[210:213], v[20:23]
	v_mfma_f32_16x16x32_bf16 v[16:19], v[168:171], v[210:213], v[16:19]
	v_mfma_f32_16x16x32_bf16 v[8:11], v[160:163], v[218:221], v[8:11]
	v_mfma_f32_16x16x32_bf16 v[0:3], v[168:171], v[218:221], v[0:3]
	v_mfma_f32_16x16x32_bf16 v[60:63], v[172:175], v[190:193], v[60:63]
	v_mfma_f32_16x16x32_bf16 v[56:59], v[180:183], v[190:193], v[56:59]
	v_mfma_f32_16x16x32_bf16 v[44:47], v[172:175], v[198:201], v[44:47]
	v_mfma_f32_16x16x32_bf16 v[40:43], v[180:183], v[198:201], v[40:43]
	v_mfma_f32_16x16x32_bf16 v[28:31], v[172:175], v[206:209], v[28:31]
	v_mfma_f32_16x16x32_bf16 v[24:27], v[180:183], v[206:209], v[24:27]
	v_mfma_f32_16x16x32_bf16 v[12:15], v[172:175], v[214:217], v[12:15]
	v_mfma_f32_16x16x32_bf16 v[4:7], v[180:183], v[214:217], v[4:7]
	v_mfma_f32_16x16x32_bf16 v[60:63], v[176:179], v[194:197], v[60:63]
	v_mfma_f32_16x16x32_bf16 v[56:59], v[184:187], v[194:197], v[56:59]
	v_mfma_f32_16x16x32_bf16 v[44:47], v[176:179], v[202:205], v[44:47]
	v_mfma_f32_16x16x32_bf16 v[40:43], v[184:187], v[202:205], v[40:43]
	v_mfma_f32_16x16x32_bf16 v[28:31], v[176:179], v[210:213], v[28:31]
	v_mfma_f32_16x16x32_bf16 v[24:27], v[184:187], v[210:213], v[24:27]
	v_mfma_f32_16x16x32_bf16 v[12:15], v[176:179], v[218:221], v[12:15]
	v_mfma_f32_16x16x32_bf16 v[4:7], v[184:187], v[218:221], v[4:7]
	s_barrier
	s_add_i32 s49, 0, 0x18000
	s_add_i32 s50, 0, 0x1c000
	v_add_u32_e32 v168, s49, v149
	v_add_u32_e32 v184, s50, v149
	ds_read_b128 v[156:159], v168
	ds_read_b128 v[160:163], v168 offset:1024
	ds_read_b128 v[164:167], v168 offset:2048
	ds_read_b128 v[168:171], v168 offset:3072
	ds_read_b128 v[172:175], v184
	ds_read_b128 v[176:179], v184 offset:1024
	ds_read_b128 v[180:183], v184 offset:2048
	ds_read_b128 v[184:187], v184 offset:3072
	s_add_u32 s24, s24, 0x80000
	s_addc_u32 s25, s25, 0
	s_mov_b32 m0, s31
	v_lshl_add_u64 v[228:229], s[24:25], 0, v[134:135]
	ds_read_b128 v[190:193], v153 offset:32768
	ds_read_b128 v[194:197], v153 offset:33792
	ds_read_b128 v[198:201], v153 offset:34816
	ds_read_b128 v[202:205], v153 offset:35840
	ds_read_b128 v[206:209], v153 offset:36864
	ds_read_b128 v[210:213], v153 offset:37888
	ds_read_b128 v[214:217], v153 offset:38912
	ds_read_b128 v[218:221], v153 offset:39936
	global_load_lds_dwordx4 v[228:229], off
	v_lshl_add_u64 v[228:229], s[24:25], 0, v[130:131]
	s_mov_b32 m0, s33
	s_nop 0
	global_load_lds_dwordx4 v[228:229], off
	s_waitcnt vmcnt(8)
	s_waitcnt lgkmcnt(0)
	s_barrier
	s_waitcnt lgkmcnt(0)
	v_mfma_f32_16x16x32_bf16 v[116:119], v[156:159], v[190:193], v[116:119]
	v_mfma_f32_16x16x32_bf16 v[112:115], v[164:167], v[190:193], v[112:115]
	v_mfma_f32_16x16x32_bf16 v[100:103], v[156:159], v[198:201], v[100:103]
	v_mfma_f32_16x16x32_bf16 v[96:99], v[164:167], v[198:201], v[96:99]
	v_mfma_f32_16x16x32_bf16 v[84:87], v[156:159], v[206:209], v[84:87]
	v_mfma_f32_16x16x32_bf16 v[80:83], v[164:167], v[206:209], v[80:83]
	v_mfma_f32_16x16x32_bf16 v[68:71], v[156:159], v[214:217], v[68:71]
	v_mfma_f32_16x16x32_bf16 v[64:67], v[164:167], v[214:217], v[64:67]
	v_mfma_f32_16x16x32_bf16 v[116:119], v[160:163], v[194:197], v[116:119]
	v_mfma_f32_16x16x32_bf16 v[112:115], v[168:171], v[194:197], v[112:115]
	v_mfma_f32_16x16x32_bf16 v[100:103], v[160:163], v[202:205], v[100:103]
	v_mfma_f32_16x16x32_bf16 v[96:99], v[168:171], v[202:205], v[96:99]
	v_mfma_f32_16x16x32_bf16 v[84:87], v[160:163], v[210:213], v[84:87]
	v_mfma_f32_16x16x32_bf16 v[80:83], v[168:171], v[210:213], v[80:83]
	v_mfma_f32_16x16x32_bf16 v[68:71], v[160:163], v[218:221], v[68:71]
	v_mfma_f32_16x16x32_bf16 v[64:67], v[168:171], v[218:221], v[64:67]
	v_mfma_f32_16x16x32_bf16 v[124:127], v[172:175], v[190:193], v[124:127]
	v_mfma_f32_16x16x32_bf16 v[120:123], v[180:183], v[190:193], v[120:123]
	v_mfma_f32_16x16x32_bf16 v[108:111], v[172:175], v[198:201], v[108:111]
	v_mfma_f32_16x16x32_bf16 v[104:107], v[180:183], v[198:201], v[104:107]
	v_mfma_f32_16x16x32_bf16 v[92:95], v[172:175], v[206:209], v[92:95]
	v_mfma_f32_16x16x32_bf16 v[88:91], v[180:183], v[206:209], v[88:91]
	v_mfma_f32_16x16x32_bf16 v[76:79], v[172:175], v[214:217], v[76:79]
	v_mfma_f32_16x16x32_bf16 v[72:75], v[180:183], v[214:217], v[72:75]
	v_mfma_f32_16x16x32_bf16 v[124:127], v[176:179], v[194:197], v[124:127]
	v_mfma_f32_16x16x32_bf16 v[120:123], v[184:187], v[194:197], v[120:123]
	v_mfma_f32_16x16x32_bf16 v[108:111], v[176:179], v[202:205], v[108:111]
	v_mfma_f32_16x16x32_bf16 v[104:107], v[184:187], v[202:205], v[104:107]
	v_mfma_f32_16x16x32_bf16 v[92:95], v[176:179], v[210:213], v[92:95]
	v_mfma_f32_16x16x32_bf16 v[88:91], v[184:187], v[210:213], v[88:91]
	v_mfma_f32_16x16x32_bf16 v[76:79], v[176:179], v[218:221], v[76:79]
	v_mfma_f32_16x16x32_bf16 v[72:75], v[184:187], v[218:221], v[72:75]
	s_barrier
	s_add_i32 s24, s49, s28
	v_lshl_add_u64 v[146:147], v[146:147], 0, s[6:7]
	s_mov_b32 m0, s24
	ds_read_b128 v[190:193], v153 offset:49152
	ds_read_b128 v[194:197], v153 offset:50176
	ds_read_b128 v[198:201], v153 offset:51200
	ds_read_b128 v[202:205], v153 offset:52224
	ds_read_b128 v[206:209], v153 offset:53248
	ds_read_b128 v[210:213], v153 offset:54272
	ds_read_b128 v[214:217], v153 offset:55296
	ds_read_b128 v[218:221], v153 offset:56320
	global_load_lds_dwordx4 v[146:147], off
	s_add_i32 m0, s24, 0x2000
	s_add_u32 s22, s22, 0x80080
	v_lshl_add_u64 v[146:147], v[222:223], 0, s[6:7]
	s_addc_u32 s23, s23, 0
	s_add_i32 s24, s50, s28
	global_load_lds_dwordx4 v[146:147], off
	v_lshl_add_u64 v[146:147], s[22:23], 0, v[132:133]
	s_mov_b32 m0, s24
	s_nop 0
	global_load_lds_dwordx4 v[146:147], off
	v_lshl_add_u64 v[146:147], s[22:23], 0, v[128:129]
	s_add_i32 m0, s24, 0x2000
	s_nop 0
	global_load_lds_dwordx4 v[146:147], off
	v_lshl_add_u64 v[146:147], v[224:225], 0, s[6:7]
	s_mov_b32 m0, s36
	s_nop 0
	global_load_lds_dwordx4 v[146:147], off
	v_lshl_add_u64 v[146:147], v[226:227], 0, s[6:7]
	s_mov_b32 m0, s37
	s_nop 0
	global_load_lds_dwordx4 v[146:147], off
	s_waitcnt vmcnt(8)
	s_waitcnt lgkmcnt(0)
	s_barrier
	s_waitcnt lgkmcnt(0)
	v_mfma_f32_16x16x32_bf16 v[52:55], v[156:159], v[190:193], v[52:55]
	v_mfma_f32_16x16x32_bf16 v[48:51], v[164:167], v[190:193], v[48:51]
	v_mfma_f32_16x16x32_bf16 v[36:39], v[156:159], v[198:201], v[36:39]
	v_mfma_f32_16x16x32_bf16 v[32:35], v[164:167], v[198:201], v[32:35]
	v_mfma_f32_16x16x32_bf16 v[20:23], v[156:159], v[206:209], v[20:23]
	v_mfma_f32_16x16x32_bf16 v[16:19], v[164:167], v[206:209], v[16:19]
	v_mfma_f32_16x16x32_bf16 v[8:11], v[156:159], v[214:217], v[8:11]
	v_mfma_f32_16x16x32_bf16 v[0:3], v[164:167], v[214:217], v[0:3]
	v_mfma_f32_16x16x32_bf16 v[52:55], v[160:163], v[194:197], v[52:55]
	v_mfma_f32_16x16x32_bf16 v[48:51], v[168:171], v[194:197], v[48:51]
	v_mfma_f32_16x16x32_bf16 v[36:39], v[160:163], v[202:205], v[36:39]
	v_mfma_f32_16x16x32_bf16 v[32:35], v[168:171], v[202:205], v[32:35]
	v_mfma_f32_16x16x32_bf16 v[20:23], v[160:163], v[210:213], v[20:23]
	v_mfma_f32_16x16x32_bf16 v[16:19], v[168:171], v[210:213], v[16:19]
	v_mfma_f32_16x16x32_bf16 v[8:11], v[160:163], v[218:221], v[8:11]
	v_mfma_f32_16x16x32_bf16 v[0:3], v[168:171], v[218:221], v[0:3]
	v_mfma_f32_16x16x32_bf16 v[60:63], v[172:175], v[190:193], v[60:63]
	v_mfma_f32_16x16x32_bf16 v[56:59], v[180:183], v[190:193], v[56:59]
	v_mfma_f32_16x16x32_bf16 v[44:47], v[172:175], v[198:201], v[44:47]
	v_mfma_f32_16x16x32_bf16 v[40:43], v[180:183], v[198:201], v[40:43]
	v_mfma_f32_16x16x32_bf16 v[28:31], v[172:175], v[206:209], v[28:31]
	v_mfma_f32_16x16x32_bf16 v[24:27], v[180:183], v[206:209], v[24:27]
	v_mfma_f32_16x16x32_bf16 v[12:15], v[172:175], v[214:217], v[12:15]
	v_mfma_f32_16x16x32_bf16 v[4:7], v[180:183], v[214:217], v[4:7]
	v_mfma_f32_16x16x32_bf16 v[60:63], v[176:179], v[194:197], v[60:63]
	v_mfma_f32_16x16x32_bf16 v[56:59], v[184:187], v[194:197], v[56:59]
	v_mfma_f32_16x16x32_bf16 v[44:47], v[176:179], v[202:205], v[44:47]
	v_mfma_f32_16x16x32_bf16 v[40:43], v[184:187], v[202:205], v[40:43]
	v_mfma_f32_16x16x32_bf16 v[28:31], v[176:179], v[210:213], v[28:31]
	v_mfma_f32_16x16x32_bf16 v[24:27], v[184:187], v[210:213], v[24:27]
	v_mfma_f32_16x16x32_bf16 v[12:15], v[176:179], v[218:221], v[12:15]
	v_mfma_f32_16x16x32_bf16 v[4:7], v[184:187], v[218:221], v[4:7]
	s_barrier
	s_add_i32 s48, s48, 2
	s_add_u32 s20, s20, 0x100
	s_addc_u32 s21, s21, 0
	s_add_u32 s46, s46, 0x100
	s_addc_u32 s47, s47, 0
	s_cmp_gt_u32 s48, 29
	s_cbranch_scc0 .LBB0_1539
	s_and_b64 vcc, exec, s[8:9]
	s_cbranch_vccz .LBB0_1542
	s_barrier

.LBB0_1624:
	ds_read_b128 v[128:131], v177
	ds_read_b128 v[132:135], v177 offset:1024
	ds_read_b128 v[136:139], v177 offset:2048
	ds_read_b128 v[140:143], v177 offset:3072
	ds_read_b128 v[160:163], v178
	ds_read_b128 v[164:167], v178 offset:1024
	ds_read_b128 v[168:171], v178 offset:2048
	ds_read_b128 v[182:185], v178 offset:3072
	s_add_u32 s20, s18, 0xffea0080
	s_addc_u32 s21, s19, -1
	s_cmpk_eq_i32 s48, 0x54
	s_cselect_b32 s23, s1, s21
	s_cselect_b32 s22, s0, s20
	s_cselect_b32 s21, s17, s47
	s_cselect_b32 s20, s16, s46
	v_lshl_add_u64 v[172:173], s[18:19], 0, v[152:153]
	s_add_i32 m0, s27, 0xc000
	ds_read_b128 v[190:193], v179
	ds_read_b128 v[194:197], v179 offset:1024
	ds_read_b128 v[198:201], v179 offset:2048
	ds_read_b128 v[202:205], v179 offset:3072
	ds_read_b128 v[206:209], v179 offset:4096
	ds_read_b128 v[210:213], v179 offset:5120
	ds_read_b128 v[214:217], v179 offset:6144
	ds_read_b128 v[218:221], v179 offset:7168
	global_load_lds_dwordx4 v[172:173], off
	v_lshl_add_u64 v[172:173], s[18:19], 0, v[154:155]
	s_add_i32 m0, s27, 0xe000
	s_nop 0
	global_load_lds_dwordx4 v[172:173], off
	s_waitcnt vmcnt(8)
	s_waitcnt lgkmcnt(0)
	s_barrier
	s_waitcnt lgkmcnt(0)
	v_mfma_f32_16x16x32_bf16 v[124:127], v[128:131], v[190:193], v[124:127]
	v_mfma_f32_16x16x32_bf16 v[120:123], v[136:139], v[190:193], v[120:123]
	v_mfma_f32_16x16x32_bf16 v[108:111], v[128:131], v[198:201], v[108:111]
	v_mfma_f32_16x16x32_bf16 v[104:107], v[136:139], v[198:201], v[104:107]
	v_mfma_f32_16x16x32_bf16 v[92:95], v[128:131], v[206:209], v[92:95]
	v_mfma_f32_16x16x32_bf16 v[88:91], v[136:139], v[206:209], v[88:91]
	v_mfma_f32_16x16x32_bf16 v[76:79], v[128:131], v[214:217], v[76:79]
	v_mfma_f32_16x16x32_bf16 v[72:75], v[136:139], v[214:217], v[72:75]
	v_mfma_f32_16x16x32_bf16 v[124:127], v[132:135], v[194:197], v[124:127]
	v_mfma_f32_16x16x32_bf16 v[120:123], v[140:143], v[194:197], v[120:123]
	v_mfma_f32_16x16x32_bf16 v[108:111], v[132:135], v[202:205], v[108:111]
	v_mfma_f32_16x16x32_bf16 v[104:107], v[140:143], v[202:205], v[104:107]
	v_mfma_f32_16x16x32_bf16 v[92:95], v[132:135], v[210:213], v[92:95]
	v_mfma_f32_16x16x32_bf16 v[88:91], v[140:143], v[210:213], v[88:91]
	v_mfma_f32_16x16x32_bf16 v[76:79], v[132:135], v[218:221], v[76:79]
	v_mfma_f32_16x16x32_bf16 v[72:75], v[140:143], v[218:221], v[72:75]
	v_mfma_f32_16x16x32_bf16 v[116:119], v[160:163], v[190:193], v[116:119]
	v_mfma_f32_16x16x32_bf16 v[112:115], v[168:171], v[190:193], v[112:115]
	v_mfma_f32_16x16x32_bf16 v[100:103], v[160:163], v[198:201], v[100:103]
	v_mfma_f32_16x16x32_bf16 v[96:99], v[168:171], v[198:201], v[96:99]
	v_mfma_f32_16x16x32_bf16 v[84:87], v[160:163], v[206:209], v[84:87]
	v_mfma_f32_16x16x32_bf16 v[80:83], v[168:171], v[206:209], v[80:83]
	v_mfma_f32_16x16x32_bf16 v[68:71], v[160:163], v[214:217], v[68:71]
	v_mfma_f32_16x16x32_bf16 v[64:67], v[168:171], v[214:217], v[64:67]
	v_mfma_f32_16x16x32_bf16 v[116:119], v[164:167], v[194:197], v[116:119]
	v_mfma_f32_16x16x32_bf16 v[112:115], v[182:185], v[194:197], v[112:115]
	v_mfma_f32_16x16x32_bf16 v[100:103], v[164:167], v[202:205], v[100:103]
	v_mfma_f32_16x16x32_bf16 v[96:99], v[182:185], v[202:205], v[96:99]
	v_mfma_f32_16x16x32_bf16 v[84:87], v[164:167], v[210:213], v[84:87]
	v_mfma_f32_16x16x32_bf16 v[80:83], v[182:185], v[210:213], v[80:83]
	v_mfma_f32_16x16x32_bf16 v[68:71], v[164:167], v[218:221], v[68:71]
	v_mfma_f32_16x16x32_bf16 v[64:67], v[182:185], v[218:221], v[64:67]
	s_barrier
	s_add_i32 s49, s39, s26
	v_lshl_add_u64 v[172:173], s[20:21], 0, v[146:147]
	s_mov_b32 m0, s49
	ds_read_b128 v[190:193], v179 offset:16384
	ds_read_b128 v[194:197], v179 offset:17408
	ds_read_b128 v[198:201], v179 offset:18432
	ds_read_b128 v[202:205], v179 offset:19456
	ds_read_b128 v[206:209], v179 offset:20480
	ds_read_b128 v[210:213], v179 offset:21504
	ds_read_b128 v[214:217], v179 offset:22528
	ds_read_b128 v[218:221], v179 offset:23552
	global_load_lds_dwordx4 v[172:173], off
	s_add_i32 m0, s49, 0x2000
	s_add_u32 s50, s20, 0x160000
	v_lshl_add_u64 v[186:187], s[20:21], 0, v[150:151]
	s_addc_u32 s51, s21, 0
	s_add_i32 s49, s40, s26
	global_load_lds_dwordx4 v[186:187], off
	v_lshl_add_u64 v[222:223], s[50:51], 0, v[146:147]
	s_mov_b32 m0, s49
	v_lshl_add_u64 v[224:225], s[22:23], 0, v[148:149]
	global_load_lds_dwordx4 v[222:223], off
	v_lshl_add_u64 v[222:223], s[50:51], 0, v[150:151]
	s_add_i32 m0, s49, 0x2000
	s_nop 0
	global_load_lds_dwordx4 v[222:223], off
	v_lshl_add_u64 v[222:223], s[22:23], 0, v[144:145]
	s_mov_b32 m0, s27
	s_nop 0
	global_load_lds_dwordx4 v[222:223], off
	s_mov_b32 m0, s28
	s_nop 0
	global_load_lds_dwordx4 v[224:225], off
	s_waitcnt vmcnt(8)
	s_waitcnt lgkmcnt(0)
	s_barrier
	s_waitcnt lgkmcnt(0)
	v_mfma_f32_16x16x32_bf16 v[60:63], v[128:131], v[190:193], v[60:63]
	v_mfma_f32_16x16x32_bf16 v[56:59], v[136:139], v[190:193], v[56:59]
	v_mfma_f32_16x16x32_bf16 v[44:47], v[128:131], v[198:201], v[44:47]
	v_mfma_f32_16x16x32_bf16 v[40:43], v[136:139], v[198:201], v[40:43]
	v_mfma_f32_16x16x32_bf16 v[28:31], v[128:131], v[206:209], v[28:31]
	v_mfma_f32_16x16x32_bf16 v[24:27], v[136:139], v[206:209], v[24:27]
	v_mfma_f32_16x16x32_bf16 v[12:15], v[128:131], v[214:217], v[12:15]
	v_mfma_f32_16x16x32_bf16 v[8:11], v[136:139], v[214:217], v[8:11]
	v_mfma_f32_16x16x32_bf16 v[60:63], v[132:135], v[194:197], v[60:63]
	v_mfma_f32_16x16x32_bf16 v[56:59], v[140:143], v[194:197], v[56:59]
	v_mfma_f32_16x16x32_bf16 v[44:47], v[132:135], v[202:205], v[44:47]
	v_mfma_f32_16x16x32_bf16 v[40:43], v[140:143], v[202:205], v[40:43]
	v_mfma_f32_16x16x32_bf16 v[28:31], v[132:135], v[210:213], v[28:31]
	v_mfma_f32_16x16x32_bf16 v[24:27], v[140:143], v[210:213], v[24:27]
	v_mfma_f32_16x16x32_bf16 v[12:15], v[132:135], v[218:221], v[12:15]
	v_mfma_f32_16x16x32_bf16 v[8:11], v[140:143], v[218:221], v[8:11]
	v_mfma_f32_16x16x32_bf16 v[52:55], v[160:163], v[190:193], v[52:55]
	v_mfma_f32_16x16x32_bf16 v[48:51], v[168:171], v[190:193], v[48:51]
	v_mfma_f32_16x16x32_bf16 v[36:39], v[160:163], v[198:201], v[36:39]
	v_mfma_f32_16x16x32_bf16 v[32:35], v[168:171], v[198:201], v[32:35]
	v_mfma_f32_16x16x32_bf16 v[20:23], v[160:163], v[206:209], v[20:23]
	v_mfma_f32_16x16x32_bf16 v[16:19], v[168:171], v[206:209], v[16:19]
	v_mfma_f32_16x16x32_bf16 v[4:7], v[160:163], v[214:217], v[4:7]
	v_mfma_f32_16x16x32_bf16 v[0:3], v[168:171], v[214:217], v[0:3]
	v_mfma_f32_16x16x32_bf16 v[52:55], v[164:167], v[194:197], v[52:55]
	v_mfma_f32_16x16x32_bf16 v[48:51], v[182:185], v[194:197], v[48:51]
	v_mfma_f32_16x16x32_bf16 v[36:39], v[164:167], v[202:205], v[36:39]
	v_mfma_f32_16x16x32_bf16 v[32:35], v[182:185], v[202:205], v[32:35]
	v_mfma_f32_16x16x32_bf16 v[20:23], v[164:167], v[210:213], v[20:23]
	v_mfma_f32_16x16x32_bf16 v[16:19], v[182:185], v[210:213], v[16:19]
	v_mfma_f32_16x16x32_bf16 v[4:7], v[164:167], v[218:221], v[4:7]
	v_mfma_f32_16x16x32_bf16 v[0:3], v[182:185], v[218:221], v[0:3]
	s_barrier
	s_add_i32 s49, 0, 0x18000
	s_add_i32 s50, 0, 0x1c000
	v_add_u32_e32 v140, s49, v175
	v_add_u32_e32 v181, s50, v175
	ds_read_b128 v[128:131], v140
	ds_read_b128 v[132:135], v140 offset:1024
	ds_read_b128 v[136:139], v140 offset:2048
	ds_read_b128 v[140:143], v140 offset:3072
	ds_read_b128 v[160:163], v181
	ds_read_b128 v[164:167], v181 offset:1024
	ds_read_b128 v[168:171], v181 offset:2048
	ds_read_b128 v[182:185], v181 offset:3072
	s_add_u32 s22, s22, 0x160000
	s_addc_u32 s23, s23, 0
	s_mov_b32 m0, s29
	v_lshl_add_u64 v[226:227], s[22:23], 0, v[144:145]
	ds_read_b128 v[190:193], v179 offset:32768
	ds_read_b128 v[194:197], v179 offset:33792
	ds_read_b128 v[198:201], v179 offset:34816
	ds_read_b128 v[202:205], v179 offset:35840
	ds_read_b128 v[206:209], v179 offset:36864
	ds_read_b128 v[210:213], v179 offset:37888
	ds_read_b128 v[214:217], v179 offset:38912
	ds_read_b128 v[218:221], v179 offset:39936
	global_load_lds_dwordx4 v[226:227], off
	v_lshl_add_u64 v[226:227], s[22:23], 0, v[148:149]
	s_mov_b32 m0, s30
	s_nop 0
	global_load_lds_dwordx4 v[226:227], off
	s_waitcnt vmcnt(8)
	s_waitcnt lgkmcnt(0)
	s_barrier
	s_waitcnt lgkmcnt(0)
	v_mfma_f32_16x16x32_bf16 v[124:127], v[128:131], v[190:193], v[124:127]
	v_mfma_f32_16x16x32_bf16 v[120:123], v[136:139], v[190:193], v[120:123]
	v_mfma_f32_16x16x32_bf16 v[108:111], v[128:131], v[198:201], v[108:111]
	v_mfma_f32_16x16x32_bf16 v[104:107], v[136:139], v[198:201], v[104:107]
	v_mfma_f32_16x16x32_bf16 v[92:95], v[128:131], v[206:209], v[92:95]
	v_mfma_f32_16x16x32_bf16 v[88:91], v[136:139], v[206:209], v[88:91]
	v_mfma_f32_16x16x32_bf16 v[76:79], v[128:131], v[214:217], v[76:79]
	v_mfma_f32_16x16x32_bf16 v[72:75], v[136:139], v[214:217], v[72:75]
	v_mfma_f32_16x16x32_bf16 v[124:127], v[132:135], v[194:197], v[124:127]
	v_mfma_f32_16x16x32_bf16 v[120:123], v[140:143], v[194:197], v[120:123]
	v_mfma_f32_16x16x32_bf16 v[108:111], v[132:135], v[202:205], v[108:111]
	v_mfma_f32_16x16x32_bf16 v[104:107], v[140:143], v[202:205], v[104:107]
	v_mfma_f32_16x16x32_bf16 v[92:95], v[132:135], v[210:213], v[92:95]
	v_mfma_f32_16x16x32_bf16 v[88:91], v[140:143], v[210:213], v[88:91]
	v_mfma_f32_16x16x32_bf16 v[76:79], v[132:135], v[218:221], v[76:79]
	v_mfma_f32_16x16x32_bf16 v[72:75], v[140:143], v[218:221], v[72:75]
	v_mfma_f32_16x16x32_bf16 v[116:119], v[160:163], v[190:193], v[116:119]
	v_mfma_f32_16x16x32_bf16 v[112:115], v[168:171], v[190:193], v[112:115]
	v_mfma_f32_16x16x32_bf16 v[100:103], v[160:163], v[198:201], v[100:103]
	v_mfma_f32_16x16x32_bf16 v[96:99], v[168:171], v[198:201], v[96:99]
	v_mfma_f32_16x16x32_bf16 v[84:87], v[160:163], v[206:209], v[84:87]
	v_mfma_f32_16x16x32_bf16 v[80:83], v[168:171], v[206:209], v[80:83]
	v_mfma_f32_16x16x32_bf16 v[68:71], v[160:163], v[214:217], v[68:71]
	v_mfma_f32_16x16x32_bf16 v[64:67], v[168:171], v[214:217], v[64:67]
	v_mfma_f32_16x16x32_bf16 v[116:119], v[164:167], v[194:197], v[116:119]
	v_mfma_f32_16x16x32_bf16 v[112:115], v[182:185], v[194:197], v[112:115]
	v_mfma_f32_16x16x32_bf16 v[100:103], v[164:167], v[202:205], v[100:103]
	v_mfma_f32_16x16x32_bf16 v[96:99], v[182:185], v[202:205], v[96:99]
	v_mfma_f32_16x16x32_bf16 v[84:87], v[164:167], v[210:213], v[84:87]
	v_mfma_f32_16x16x32_bf16 v[80:83], v[182:185], v[210:213], v[80:83]
	v_mfma_f32_16x16x32_bf16 v[68:71], v[164:167], v[218:221], v[68:71]
	v_mfma_f32_16x16x32_bf16 v[64:67], v[182:185], v[218:221], v[64:67]
	s_barrier
	s_add_i32 s22, s49, s26
	v_lshl_add_u64 v[172:173], v[172:173], 0, s[10:11]
	s_mov_b32 m0, s22
	ds_read_b128 v[190:193], v179 offset:49152
	ds_read_b128 v[194:197], v179 offset:50176
	ds_read_b128 v[198:201], v179 offset:51200
	ds_read_b128 v[202:205], v179 offset:52224
	ds_read_b128 v[206:209], v179 offset:53248
	ds_read_b128 v[210:213], v179 offset:54272
	ds_read_b128 v[214:217], v179 offset:55296
	ds_read_b128 v[218:221], v179 offset:56320
	global_load_lds_dwordx4 v[172:173], off
	s_add_i32 m0, s22, 0x2000
	s_add_u32 s20, s20, 0x160080
	v_lshl_add_u64 v[172:173], v[186:187], 0, s[10:11]
	s_addc_u32 s21, s21, 0
	s_add_i32 s22, s50, s26
	global_load_lds_dwordx4 v[172:173], off
	v_lshl_add_u64 v[172:173], s[20:21], 0, v[146:147]
	s_mov_b32 m0, s22
	s_nop 0
	global_load_lds_dwordx4 v[172:173], off
	v_lshl_add_u64 v[172:173], s[20:21], 0, v[150:151]
	s_add_i32 m0, s22, 0x2000
	s_nop 0
	global_load_lds_dwordx4 v[172:173], off
	v_lshl_add_u64 v[172:173], v[222:223], 0, s[10:11]
	s_mov_b32 m0, s35
	s_nop 0
	global_load_lds_dwordx4 v[172:173], off
	v_lshl_add_u64 v[172:173], v[224:225], 0, s[10:11]
	s_mov_b32 m0, s36
	s_nop 0
	global_load_lds_dwordx4 v[172:173], off
	s_waitcnt vmcnt(8)
	s_waitcnt lgkmcnt(0)
	s_barrier
	s_waitcnt lgkmcnt(0)
	v_mfma_f32_16x16x32_bf16 v[60:63], v[128:131], v[190:193], v[60:63]
	v_mfma_f32_16x16x32_bf16 v[56:59], v[136:139], v[190:193], v[56:59]
	v_mfma_f32_16x16x32_bf16 v[44:47], v[128:131], v[198:201], v[44:47]
	v_mfma_f32_16x16x32_bf16 v[40:43], v[136:139], v[198:201], v[40:43]
	v_mfma_f32_16x16x32_bf16 v[28:31], v[128:131], v[206:209], v[28:31]
	v_mfma_f32_16x16x32_bf16 v[24:27], v[136:139], v[206:209], v[24:27]
	v_mfma_f32_16x16x32_bf16 v[12:15], v[128:131], v[214:217], v[12:15]
	v_mfma_f32_16x16x32_bf16 v[8:11], v[136:139], v[214:217], v[8:11]
	v_mfma_f32_16x16x32_bf16 v[60:63], v[132:135], v[194:197], v[60:63]
	v_mfma_f32_16x16x32_bf16 v[56:59], v[140:143], v[194:197], v[56:59]
	v_mfma_f32_16x16x32_bf16 v[44:47], v[132:135], v[202:205], v[44:47]
	v_mfma_f32_16x16x32_bf16 v[40:43], v[140:143], v[202:205], v[40:43]
	v_mfma_f32_16x16x32_bf16 v[28:31], v[132:135], v[210:213], v[28:31]
	v_mfma_f32_16x16x32_bf16 v[24:27], v[140:143], v[210:213], v[24:27]
	v_mfma_f32_16x16x32_bf16 v[12:15], v[132:135], v[218:221], v[12:15]
	v_mfma_f32_16x16x32_bf16 v[8:11], v[140:143], v[218:221], v[8:11]
	v_mfma_f32_16x16x32_bf16 v[52:55], v[160:163], v[190:193], v[52:55]
	v_mfma_f32_16x16x32_bf16 v[48:51], v[168:171], v[190:193], v[48:51]
	v_mfma_f32_16x16x32_bf16 v[36:39], v[160:163], v[198:201], v[36:39]
	v_mfma_f32_16x16x32_bf16 v[32:35], v[168:171], v[198:201], v[32:35]
	v_mfma_f32_16x16x32_bf16 v[20:23], v[160:163], v[206:209], v[20:23]
	v_mfma_f32_16x16x32_bf16 v[16:19], v[168:171], v[206:209], v[16:19]
	v_mfma_f32_16x16x32_bf16 v[4:7], v[160:163], v[214:217], v[4:7]
	v_mfma_f32_16x16x32_bf16 v[0:3], v[168:171], v[214:217], v[0:3]
	v_mfma_f32_16x16x32_bf16 v[52:55], v[164:167], v[194:197], v[52:55]
	v_mfma_f32_16x16x32_bf16 v[48:51], v[182:185], v[194:197], v[48:51]
	v_mfma_f32_16x16x32_bf16 v[36:39], v[164:167], v[202:205], v[36:39]
	v_mfma_f32_16x16x32_bf16 v[32:35], v[182:185], v[202:205], v[32:35]
	v_mfma_f32_16x16x32_bf16 v[20:23], v[164:167], v[210:213], v[20:23]
	v_mfma_f32_16x16x32_bf16 v[16:19], v[182:185], v[210:213], v[16:19]
	v_mfma_f32_16x16x32_bf16 v[4:7], v[164:167], v[218:221], v[4:7]
	v_mfma_f32_16x16x32_bf16 v[0:3], v[182:185], v[218:221], v[0:3]
	s_barrier
	s_add_i32 s48, s48, 2
	s_add_u32 s18, s18, 0x100
	s_addc_u32 s19, s19, 0
	s_add_u32 s46, s46, 0x100
	s_addc_u32 s47, s47, 0
	s_cmpk_gt_u32 s48, 0x55
	s_cbranch_scc0 .LBB0_1624
	s_and_b64 vcc, exec, s[12:13]
	s_cbranch_vccz .LBB0_1627
	s_barrier
